# attA: per-row exponent reference folded into the MFMA C block (rebuilt exactly per pair in the last PV shadow), so the first score chain needs no offset adds; all loop adds scalar
# speedup vs baseline: 1.0130x; 1.0015x over previous
; __device__ __forceinline__ void unit(LAS unsigned char* lds, bf16_t* P1, const bf16_t* vaT, int b, int h, int qblk, float lam, const float* subln_w, const float* khalf) {
;     ...
;     const int qrow = qblk * 128 + qs * 32 + r32;
;     const size_t rowbase = (size_t)b * SEQ;
;     bf16x8 qf[4];
;     { const bf16_t* qp = P1 + (rowbase + qrow) * LDP + C_QA + (2 * h + mi) * 64 + hi * 8;
; #pragma unroll
;       for (int ks = 0; ks < 4; ++ks) qf[ks] = *(const bf16x8*)(qp + ks * 16); }
;     const float sl2 = ex2(-(float)(h + 1)) * LOG2E;
;     const float sl2h = sl2 * (float)(4 * hi);
;     float qbound;
;     { float q2 = 0.f;
; #pragma unroll
;       for (int ks = 0; ks < 4; ++ks)
; #pragma unroll
;           for (int e = 0; e < 8; ++e) { const float v = __uint_as_float((unsigned)(unsigned short)qf[ks][e] << 16); q2 += v * v; }
;       q2 += __shfl_xor(q2, 32);
;       const float* kh = khalf + (b * 16 + 2 * h + mi) * 2;
;       qbound = sqrtf(q2 * (kh[0] + kh[1])) * 1.01f + 0.05f; }
;     volatile LAS int* dflag = (volatile LAS int*)(lds + 4 * STG);
;     f32x16 O[4];
; #pragma unroll
;     for (int d = 0; d < 4; ++d)
; #pragma unroll
;         for (int r = 0; r < 16; ++r) O[d][r] = 0.f;
;     float m = -INFINITY, l = 0.f;
;     const int NT = 2 * qblk + 2;
;     const char* kbase = (const char*)(P1 + rowbase * LDP + C_KA + h * 128);
;     const char* vbase = (const char*)(vaT + (size_t)(h * 128) * MTOK + rowbase);
;     unsigned kso0, kso1, vso0, vso1;
;     { const int rk0 = (2 * wid) * 4 + (lane >> 4), rk1 = rk0 + 4, sl = lane & 15;
;       kso0 = (unsigned)((rk0 * LDP + ((sl ^ (rk0 & 15)) * 8)) * 2); kso1 = (unsigned)((rk1 * LDP + ((sl ^ (rk1 & 15)) * 8)) * 2);
;       const int d0 = (2 * wid) * 8 + (lane >> 3), d1 = d0 + 8, sv = lane & 7;
;       vso0 = (unsigned)((d0 * MTOK + ((sv ^ ((d0 >> 1) & 7)) * 8)) * 2); vso1 = (unsigned)((d1 * MTOK + ((sv ^ ((d1 >> 1) & 7)) * 8)) * 2); }
;     ...
;     unsigned koff[4], voff[4];
; #pragma unroll
;     for (int ks = 0; ks < 4; ++ks) koff[ks] = (unsigned)(r32 * 256 + (((mi * 8 + 2 * ks + hi) ^ (r32 & 15)) * 16));
; #pragma unroll
;     for (int q = 0; q < 4; ++q) voff[q] = (unsigned)(VOFF + r32 * 128 + (((2 * q + hi) ^ ((r32 >> 1) & 7)) * 16));
;     DMA_TILE(NT - 1, 0); DMA_TILE(NT - 2, 1); if (NT > 2) DMA_TILE(NT - 3, 2);
;     int stg = 0;
;     ...
;         { float slv = sl2; asm volatile("" : "+v"(slv));
; #pragma unroll
.LBB0_397:
	s_add_i32 s2, s4, 1
	v_cvt_f32_u32_e32 v0, s2
	s_waitcnt lgkmcnt(0)
	v_add_f32_e32 v4, v13, v14
	v_add_f32_e32 v2, v2, v3
	v_mul_f32_e32 v2, v2, v4
	s_mov_b32 s2, 0xf800000
	v_mul_f32_e32 v3, 0x4f800000, v2
	v_cmp_gt_f32_e32 vcc, s2, v2
	v_exp_f32_e64 v0, -v0
	s_add_i32 s73, s71, 2
	v_cndmask_b32_e32 v2, v2, v3, vcc
	v_sqrt_f32_e32 v3, v2
	v_mul_f32_e32 v127, 0x3fb8aa3b, v0
	s_add_i32 s75, s71, 1
	v_mov_b32_e32 v14, v1
	v_add_u32_e32 v0, -1, v3
	v_fma_f32 v4, -v0, v3, v2
	v_cmp_ge_f32_e64 s[2:3], 0, v4
	v_add_u32_e32 v4, 1, v3
	v_mov_b32_e32 v15, v1
	v_cndmask_b32_e64 v0, v3, v0, s[2:3]
	v_fma_f32 v3, -v4, v3, v2
	v_cmp_lt_f32_e64 s[2:3], 0, v3
	v_mov_b32_e32 v5, v1
	v_mov_b32_e32 v6, v1
	v_cndmask_b32_e64 v0, v0, v4, s[2:3]
	v_mul_f32_e32 v3, 0x37800000, v0
	v_cndmask_b32_e32 v0, v0, v3, vcc
	v_cmp_class_f32_e32 vcc, v2, v178
	s_lshl_b32 s2, s70, 3
	v_bitop3_b32 v3, s2, v148, v144 bitop3:0x36
	v_cndmask_b32_e32 v0, v0, v2, vcc
	v_or_b32_e32 v2, s2, v144
	s_lshl_b32 s2, s77, 2
	s_add_i32 s74, s2, 0
	s_add_i32 s74, s74, 0x20000
	s_lshl_b32 s2, s77, 19
	s_add_u32 s3, s44, s81
	s_addc_u32 s44, s45, 0
	s_andn2_b32 s5, 31, s5
	s_lshl_b32 s45, s5, 8
	s_add_u32 s3, s3, s45
	s_addc_u32 s45, s44, 0
	s_add_u32 s44, s66, s3
	s_addc_u32 s45, s67, s45
	s_mul_i32 s5, s5, 0x1a0000
	v_fmamk_f32 v132, v0, 0x3f8147ae, v179
	v_or_b32_e32 v0, s2, v172
	s_add_u32 s80, s80, s5
	s_mov_b32 s5, s11
	v_lshl_add_u64 v[134:135], v[0:1], 0, s[20:21]
	v_or_b32_e32 v0, s2, v173
	s_addc_u32 s81, 0, 0
	s_lshl_b64 s[2:3], s[4:5], 8
	s_add_u32 s2, s80, s2
	v_add_u32_e32 v0, v0, v12
	s_addc_u32 s3, s81, s3
	s_mul_i32 s4, s77, 0xd000
	v_lshl_add_u64 v[136:137], v[0:1], 0, s[20:21]
	v_add_u32_e32 v0, s4, v174
	s_add_u32 s2, s48, s2
	v_lshlrev_b32_e32 v129, 4, v3
	v_bitop3_b32 v3, v2, v148, 2 bitop3:0x36
	v_add_lshl_u32 v0, v0, v10, 1
	s_addc_u32 s3, s49, s3
	s_mul_i32 s77, s77, 0x1a000
	v_lshlrev_b32_e32 v185, 4, v3
	v_bitop3_b32 v3, v2, v148, 4 bitop3:0x36
	v_bitop3_b32 v2, v2, v148, 6 bitop3:0x36
	v_lshl_add_u64 v[138:139], s[2:3], 0, v[0:1]
	v_add3_u32 v0, v175, s77, v11
	v_lshlrev_b32_e32 v186, 4, v3
	v_lshlrev_b32_e32 v187, 4, v2
	v_lshl_add_u64 v[140:141], s[2:3], 0, v[0:1]
	v_mov_b32_e32 v0, v1
	v_mov_b32_e32 v2, v1
	v_mov_b32_e32 v3, v1
	v_mov_b32_e32 v4, v1
	v_mov_b32_e32 v7, v1
	v_mov_b32_e32 v8, v1
	v_mov_b32_e32 v9, v1
	v_mov_b32_e32 v10, v1
	v_mov_b32_e32 v11, v1
	v_mov_b32_e32 v12, v1
	v_mov_b32_e32 v13, v1
	v_mov_b64_e32 v[64:65], v[14:15]
	v_mov_b64_e32 v[48:49], v[14:15]
	v_mov_b64_e32 v[32:33], v[14:15]
	v_mul_f32_e32 v130, v127, v146
	v_mov_b64_e32 v[62:63], v[12:13]
	v_mov_b64_e32 v[60:61], v[10:11]
	v_mov_b64_e32 v[58:59], v[8:9]
	v_mov_b64_e32 v[56:57], v[6:7]
	v_mov_b64_e32 v[54:55], v[4:5]
	v_mov_b64_e32 v[52:53], v[2:3]
	v_mov_b64_e32 v[50:51], v[0:1]
	v_mov_b64_e32 v[46:47], v[12:13]
	v_mov_b64_e32 v[44:45], v[10:11]
	v_mov_b64_e32 v[42:43], v[8:9]
	v_mov_b64_e32 v[40:41], v[6:7]
	v_mov_b64_e32 v[38:39], v[4:5]
	v_mov_b64_e32 v[36:37], v[2:3]
	v_mov_b64_e32 v[34:35], v[0:1]
	v_mov_b64_e32 v[30:31], v[12:13]
	v_mov_b64_e32 v[28:29], v[10:11]
	v_mov_b64_e32 v[26:27], v[8:9]
	v_mov_b64_e32 v[24:25], v[6:7]
	v_mov_b64_e32 v[22:23], v[4:5]
	v_mov_b64_e32 v[20:21], v[2:3]
	v_mov_b64_e32 v[18:19], v[0:1]
	v_mov_b64_e32 v[16:17], v[14:15]
	s_mov_b32 s10, 0
	v_mul_f32_e32 v188, 0x42000000, v127
	v_mov_b32_e32 v131, v130
	v_add_u32_e32 v189, s59, v145
	v_subrev_u32_e32 v190, s76, v177
	v_mov_b32_e32 v191, 0
	v_mov_b32_e32 v133, 0xff800000
	s_mov_b32 s76, 0
	s_mov_b32 s77, 0
	v_mov_b64_e32 v[14:15], v[12:13]
	v_mov_b64_e32 v[12:13], v[10:11]
	v_mov_b64_e32 v[10:11], v[8:9]
	v_mov_b64_e32 v[8:9], v[6:7]
	v_mov_b64_e32 v[6:7], v[4:5]
	v_mov_b64_e32 v[4:5], v[2:3]
	v_mov_b64_e32 v[2:3], v[0:1]
	s_mov_b32 s80, 0
	s_mov_b32 s81, 0
	v_add_u32_e32 v137, s76, v190
	v_add_u32_e32 v137, 64, v137
	v_cvt_f32_i32_e32 v137, v137
	v_fma_f32 v248, v127, v137, -v132
	v_add_f32_e32 v248, v130, v248
	v_mov_b32_e32 v226, v248
	v_add_f32_e32 v227, v248, v127
	v_fma_f32 v228, v127, s22, v248
	v_fma_f32 v229, v127, s23, v248
	v_fma_f32 v230, v127, s24, v248
	v_fma_f32 v231, v127, s25, v248
	v_fma_f32 v232, v127, s26, v248
	v_fma_f32 v233, v127, s27, v248
	v_fma_f32 v234, v127, s28, v248
	v_fma_f32 v235, v127, s29, v248
	v_fma_f32 v236, v127, s30, v248
	v_fma_f32 v237, v127, s31, v248
	v_fma_f32 v238, v127, s34, v248
	v_fma_f32 v239, v127, s35, v248
	v_fma_f32 v240, v127, s36, v248
	v_fma_f32 v241, v127, s37, v248
	v_mul_f32_e32 v131, -2.0, v188

; #define LAS __attribute__((address_space(3)))
; __device__ __forceinline__ int crow(int r, int hi) { return (r & 3) + 8 * (r >> 2) + 4 * hi; }
; __device__ __forceinline__ void unit(LAS unsigned char* lds, bf16_t* P1, const bf16_t* vaT, int b, int h, int qblk, float lam, const float* subln_w, const float* khalf) {
;     ...
;         { const bool done = __all(qbound + sl2 * (float)(64 * j + 63 - qrow) < m - 24.f);
;           if (lane == 0) dflag[(jj & 1) * 8 + wid] = done ? 1 : 0; }
;         if (jj + 2 < NT) asm volatile("s_waitcnt vmcnt(8) lgkmcnt(0)\n\ts_barrier" ::: "memory"); else if (jj + 1 < NT) asm volatile("s_waitcnt vmcnt(4) lgkmcnt(0)\n\ts_barrier" ::: "memory"); else asm volatile("s_waitcnt vmcnt(0) lgkmcnt(0)\n\ts_barrier" ::: "memory");
;         { typedef int i32x4 __attribute__((ext_vector_type(4)));
;           const i32x4 fa = *(const LAS i32x4*)(lds + 4 * STG + (jj & 1) * 32), fb = *(const LAS i32x4*)(lds + 4 * STG + (jj & 1) * 32 + 16);
;           if (((fa[0] + fa[1]) + (fa[2] + fa[3])) + ((fb[0] + fb[1]) + (fb[2] + fb[3])) == 8) break; }
;         if (jj + 3 < NT) { DMA_TILE(j - 3, (stg + 3) & 3); }
;         const LAS unsigned char* kb = lds + stg * STG;
;         stg = (stg + 1) & 3;
;         f32x16 S0, S1;
;         { float slv = sl2; asm volatile("" : "+v"(slv));
; #pragma unroll
;           for (int r = 0; r < 16; ++r) { S0[r] = __builtin_fmaf(slv, (float)((r & 3) + 8 * (r >> 2)), sl2h); S1[r] = S0[r]; } }
; #pragma unroll
;         for (int ks = 0; ks < 4; ++ks) {
;             const bf16x8 a0 = *(const LAS bf16x8*)(kb + koff[ks]);
;             const bf16x8 a1 = *(const LAS bf16x8*)(kb + koff[ks] + 32 * 256);
;             S0 = MFMA32(a0, qf[ks], S0); S1 = MFMA32(a1, qf[ks], S1);
;         }
;         const int kv0 = 64 * j;
;         if (j >= NT - 2) {
; #pragma unroll
;             for (int r = 0; r < 16; ++r) { const int kv = kv0 + crow(r, hi); if (kv > qrow) S0[r] = -INFINITY; if (kv + 32 > qrow) S1[r] = -INFINITY; }
;         }
;         const float tb0 = sl2 * (float)(kv0 - qrow), tb1 = tb0 + sl2 * 32.f;
;         float mx0 = S0[0], mx1 = S1[0];
; #pragma unroll
;         for (int r = 1; r < 16; ++r) { mx0 = fmaxf(mx0, S0[r]); mx1 = fmaxf(mx1, S1[r]); }
;         float mt = fmaxf(mx0 + tb0, mx1 + tb1); mt = fmaxf(mt, __shfl_xor(mt, 32));
;         const bool skip = __all((mt < m - 24.f) || (mt == -INFINITY));
.La_after_bar0:
	s_lshl_b32 s82, s80, 15
	s_add_i32 s83, s82, 0x8000
	s_sub_i32 s100, s76, 64
	s_and_b32 s2, s81, 2
	s_lshl_b32 s2, s2, 4
	s_add_i32 s2, s2, 0x20000
	v_mov_b32_e32 v70, s2
	ds_read_b128 v[66:69], v70
	ds_read_b128 v[70:73], v70 offset:16
	v_add3_u32 v201, s82, v129, v151
	v_add3_u32 v135, s82, v185, v151
	v_add3_u32 v249, s82, v186, v151
	v_add3_u32 v254, s82, v187, v151
	ds_read_b128 v[192:195], v201
	ds_read_b128 v[202:205], v135
	ds_read_b128 v[210:213], v249
	ds_read_b128 v[218:221], v254
	ds_read_b128 v[196:199], v201 offset:8192
	ds_read_b128 v[206:209], v135 offset:8192
	ds_read_b128 v[214:217], v249 offset:8192
	ds_read_b128 v[222:225], v254 offset:8192
	s_waitcnt lgkmcnt(8)
	v_add3_u32 v66, v66, v67, v68
	v_add3_u32 v69, v69, v70, v71
	v_add_u32_e32 v72, v72, v73
	v_add3_u32 v66, v66, v69, v72
	v_cmp_eq_u32_e32 vcc, 8, v66
	s_cbranch_vccnz .LBB0_420
	s_waitcnt lgkmcnt(4)
	v_mfma_f32_32x32x16_bf16 v[82:97], v[192:195], v[98:101], v[226:241]
	v_add_u32_e32 v244, s82, v168
	v_add_u32_e32 v245, s82, v169
	v_mfma_f32_32x32x16_bf16 v[82:97], v[202:205], v[102:105], v[82:97]
	v_add_u32_e32 v246, s82, v170
	v_add_u32_e32 v247, s82, v171
	v_mfma_f32_32x32x16_bf16 v[82:97], v[210:213], v[106:109], v[82:97]
	v_add_f32_e32 v143, v133, v121
	v_max_f32_e32 v143, 0xff7fffff, v143
	v_mfma_f32_32x32x16_bf16 v[82:97], v[218:221], v[110:113], v[82:97]
	ds_read_b128 v[192:195], v244 offset:16384
	ds_read_b128 v[202:205], v244 offset:20480
	ds_read_b128 v[210:213], v244 offset:24576
	ds_read_b128 v[218:221], v244 offset:28672
	s_waitcnt lgkmcnt(4)
	v_mfma_f32_32x32x16_bf16 v[66:81], v[196:199], v[98:101], v[226:241]
	v_mfma_f32_32x32x16_bf16 v[66:81], v[206:209], v[102:105], v[66:81]
	v_max3_f32 v0, v82, v83, v84
	v_max3_f32 v0, v0, v85, v86
	v_mfma_f32_32x32x16_bf16 v[66:81], v[214:217], v[106:109], v[66:81]
	v_max3_f32 v0, v0, v87, v88
	v_max3_f32 v0, v0, v89, v90
	v_max3_f32 v0, v0, v91, v92
	v_mfma_f32_32x32x16_bf16 v[66:81], v[222:225], v[110:113], v[66:81]
	v_max3_f32 v0, v0, v93, v94
	v_max3_f32 v0, v0, v95, v96
	v_max_f32_e32 v0, v0, v97
	ds_read_b128 v[196:199], v245 offset:16384
	ds_read_b128 v[206:209], v245 offset:20480
	ds_read_b128 v[214:217], v245 offset:24576
	ds_read_b128 v[222:225], v245 offset:28672
	s_nop 3
	v_add_u32_e32 v243, s76, v189
	v_add_u32_e32 v250, 0x60, v243
	v_add_u32_e32 v251, 64, v243
	v_cmp_le_i32_e32 vcc, v250, v125
	s_nop 6
	v_cndmask_b32_e32 v66, v184, v66, vcc
	v_cmp_lt_i32_e32 vcc, v251, v125
	s_nop 1
	v_cndmask_b32_e32 v83, v184, v83, vcc
	v_cmp_le_i32_e32 vcc, v251, v125
	v_add_u32_e32 v251, 0x61, v243
	s_nop 0
	v_cndmask_b32_e32 v82, v184, v82, vcc
	v_cmp_le_i32_e32 vcc, v251, v125
	v_add_u32_e32 v251, 0x42, v243
	s_nop 0
	v_cndmask_b32_e32 v67, v184, v67, vcc
	v_cmp_le_i32_e32 vcc, v251, v125
	v_add_u32_e32 v251, 0x62, v243
	s_nop 0
	v_cndmask_b32_e32 v84, v184, v84, vcc
	v_cmp_le_i32_e32 vcc, v251, v125
	v_add_u32_e32 v251, 0x43, v243
	s_nop 0
	v_cndmask_b32_e32 v68, v184, v68, vcc
	v_cmp_le_i32_e32 vcc, v251, v125
	v_add_u32_e32 v251, 0x63, v243
	s_nop 0
	v_cndmask_b32_e32 v85, v184, v85, vcc
	v_cmp_le_i32_e32 vcc, v251, v125
	v_add_u32_e32 v251, 0x48, v243
	s_nop 0
	v_cndmask_b32_e32 v69, v184, v69, vcc
	v_cmp_le_i32_e32 vcc, v251, v125
	v_add_u32_e32 v251, 0x68, v243
	s_nop 0
	v_cndmask_b32_e32 v86, v184, v86, vcc
	v_cmp_le_i32_e32 vcc, v251, v125
	v_add_u32_e32 v251, 0x49, v243
	s_nop 0
	v_cndmask_b32_e32 v70, v184, v70, vcc
	v_cmp_le_i32_e32 vcc, v251, v125
	v_add_u32_e32 v251, 0x69, v243
	s_nop 0
	v_cndmask_b32_e32 v87, v184, v87, vcc
	v_cmp_le_i32_e32 vcc, v251, v125
	v_add_u32_e32 v251, 0x4a, v243
	s_nop 0
	v_cndmask_b32_e32 v71, v184, v71, vcc
	v_cmp_le_i32_e32 vcc, v251, v125
	v_add_u32_e32 v251, 0x6a, v243
	s_nop 0
	v_cndmask_b32_e32 v88, v184, v88, vcc
	v_cmp_le_i32_e32 vcc, v251, v125
	v_add_u32_e32 v251, 0x4b, v243
	s_nop 0
	v_cndmask_b32_e32 v72, v184, v72, vcc
	v_cmp_le_i32_e32 vcc, v251, v125
	v_add_u32_e32 v251, 0x6b, v243
	s_nop 0
	v_cndmask_b32_e32 v89, v184, v89, vcc
	v_cmp_le_i32_e32 vcc, v251, v125
	v_add_u32_e32 v251, 0x50, v243
	s_nop 0
	v_cndmask_b32_e32 v73, v184, v73, vcc
	v_cmp_le_i32_e32 vcc, v251, v125
	v_add_u32_e32 v251, 0x70, v243
	s_nop 0
	v_cndmask_b32_e32 v90, v184, v90, vcc
	v_cmp_le_i32_e32 vcc, v251, v125
	v_add_u32_e32 v251, 0x51, v243
	s_nop 0
	v_cndmask_b32_e32 v74, v184, v74, vcc
	v_cmp_le_i32_e32 vcc, v251, v125
	v_add_u32_e32 v251, 0x71, v243
	s_nop 0
	v_cndmask_b32_e32 v91, v184, v91, vcc
	v_cmp_le_i32_e32 vcc, v251, v125
	v_add_u32_e32 v251, 0x52, v243
	s_nop 0
	v_cndmask_b32_e32 v75, v184, v75, vcc
	v_cmp_le_i32_e32 vcc, v251, v125
	v_add_u32_e32 v251, 0x72, v243
	s_nop 0
	v_cndmask_b32_e32 v92, v184, v92, vcc
	v_cmp_le_i32_e32 vcc, v251, v125
	v_add_u32_e32 v251, 0x53, v243
	s_nop 0
	v_cndmask_b32_e32 v76, v184, v76, vcc
	v_cmp_le_i32_e32 vcc, v251, v125
	v_add_u32_e32 v251, 0x73, v243
	s_nop 0
	v_cndmask_b32_e32 v93, v184, v93, vcc
	v_cmp_le_i32_e32 vcc, v251, v125
	v_add_u32_e32 v251, 0x58, v243
	s_nop 0
	v_cndmask_b32_e32 v77, v184, v77, vcc
	v_cmp_le_i32_e32 vcc, v251, v125
	v_add_u32_e32 v251, 0x78, v243
	s_nop 0
	v_cndmask_b32_e32 v94, v184, v94, vcc
	v_cmp_le_i32_e32 vcc, v251, v125
	v_add_u32_e32 v251, 0x59, v243
	s_nop 0
	v_cndmask_b32_e32 v78, v184, v78, vcc
	v_cmp_le_i32_e32 vcc, v251, v125
	v_add_u32_e32 v251, 0x79, v243
	s_nop 0
	v_cndmask_b32_e32 v95, v184, v95, vcc
	v_cmp_le_i32_e32 vcc, v251, v125
	v_add_u32_e32 v251, 0x5a, v243
	s_nop 0
	v_cndmask_b32_e32 v79, v184, v79, vcc
	v_cmp_le_i32_e32 vcc, v251, v125
	v_add_u32_e32 v251, 0x7a, v243
	s_nop 0
	v_cndmask_b32_e32 v96, v184, v96, vcc
	v_cmp_le_i32_e32 vcc, v251, v125
	v_add_u32_e32 v251, 0x5b, v243
	v_add_u32_e32 v243, 0x7b, v243
	v_cndmask_b32_e32 v80, v184, v80, vcc
	v_cmp_le_i32_e32 vcc, v251, v125
	s_nop 1
	v_cndmask_b32_e32 v97, v184, v97, vcc
	v_cmp_le_i32_e32 vcc, v243, v125
	s_nop 1
	v_cndmask_b32_e32 v81, v184, v81, vcc
	v_max3_f32 v0, v82, v83, v84
	v_max3_f32 v0, v0, v85, v86
	v_max3_f32 v0, v0, v87, v88
	v_max3_f32 v0, v0, v89, v90
	v_max3_f32 v0, v0, v91, v92
	v_max3_f32 v0, v0, v93, v94
	v_max3_f32 v0, v0, v95, v96
	v_max_f32_e32 v0, v0, v97
	s_nop 1
	v_max3_f32 v120, v66, v67, v68
	v_max3_f32 v120, v120, v69, v70
	v_max3_f32 v120, v120, v71, v72
	v_max3_f32 v120, v120, v73, v74
	v_max3_f32 v120, v120, v75, v76
	v_max3_f32 v120, v120, v77, v78
	v_max3_f32 v120, v120, v79, v80
	v_max_f32_e32 v120, v120, v81
	v_add_f32_e32 v120, v188, v120
	v_max_f32_e32 v0, v0, v120
	v_add_f32_e32 v0, v132, v0
	v_mov_b32_e32 v120, v0
	s_nop 1
	v_permlane32_swap_b32_e32 v0, v120
	v_max_f32_e32 v0, v0, v120
	v_cmp_lt_f32_e32 vcc, v0, v143
	v_max_f32_e32 v133, v133, v0
	v_mov_b32_e32 v255, v0
	s_andn2_b64 s[2:3], exec, vcc
	s_cbranch_scc0 .La_skipA0
; #define LAS __attribute__((address_space(3)))
; __device__ __forceinline__ unsigned cvtpk(float lo, float hi) { return pg8::cvt_pk_bf16(lo, hi); }
; __device__ __forceinline__ float ex2(float v) { return __builtin_amdgcn_exp2f(v); }
; #define MFMA32(a, b, c) __builtin_amdgcn_mfma_f32_32x32x16_bf16((a), (b), (c), 0, 0, 0)
; __device__ __forceinline__ void unit(LAS unsigned char* lds, bf16_t* P1, const bf16_t* vaT, int b, int h, int qblk, float lam, const float* subln_w, const float* khalf) {
;     ...
;         { float slv = sl2; asm volatile("" : "+v"(slv));
; #pragma unroll
;           for (int r = 0; r < 16; ++r) { S0[r] = __builtin_fmaf(slv, (float)((r & 3) + 8 * (r >> 2)), sl2h); S1[r] = S0[r]; } }
;     ...
;         for (int r = 0; r < 16; r += 2) { f32x2 a = (f32x2){S0[r], S0[r + 1]} + c0, bq = (f32x2){S1[r], S1[r + 1]} + c1;
;             a.x = ex2(a.x); a.y = ex2(a.y); bq.x = ex2(bq.x); bq.y = ex2(bq.y); S0[r] = a.x; S0[r + 1] = a.y; S1[r] = bq.x; S1[r + 1] = bq.y; ps2 = ps2 + a; ps2 = ps2 + bq; }
;         l = l * alpha + (ps2.x + ps2.y);
;         if (__any(alpha != 1.f)) {
; #pragma unroll
;             for (int d = 0; d < 4; ++d) O[d] = O[d] * alpha;
;         }
;         u32x4 pk[2][2];
; #pragma unroll
;         for (int s = 0; s < 2; ++s) {
;             pk[0][s] = (u32x4){cvtpk(S0[8 * s + 0], S0[8 * s + 1]), cvtpk(S0[8 * s + 2], S0[8 * s + 3]), cvtpk(S0[8 * s + 4], S0[8 * s + 5]), cvtpk(S0[8 * s + 6], S0[8 * s + 7])};
;             pk[1][s] = (u32x4){cvtpk(S1[8 * s + 0], S1[8 * s + 1]), cvtpk(S1[8 * s + 2], S1[8 * s + 3]), cvtpk(S1[8 * s + 4], S1[8 * s + 5]), cvtpk(S1[8 * s + 6], S1[8 * s + 7])};
;         }
; #pragma unroll
;         for (int d = 0; d < 4; ++d)
; #pragma unroll
;             for (int t2 = 0; t2 < 2; ++t2)
; #pragma unroll
;                 for (int s = 0; s < 2; ++s) {
;                     const bf16x8 vf = *(const LAS bf16x8*)(kb + voff[2 * t2 + s] + d * 32 * 128);
;                     O[d] = MFMA32(vf, __builtin_bit_cast(bf16x8, pk[t2][s]), O[d]);
;                 }
	v_exp_f32_e32 v82, v82
	v_exp_f32_e32 v83, v83
	v_exp_f32_e32 v84, v84
	v_exp_f32_e32 v85, v85
	v_exp_f32_e32 v86, v86
	v_exp_f32_e32 v87, v87
	v_exp_f32_e32 v88, v88
	v_exp_f32_e32 v89, v89
	v_add_f32_e32 v252, v82, v84
	v_add_f32_e32 v253, v83, v85
	v_cvt_pk_bf16_f32 v82, v82, v83
	v_cvt_pk_bf16_f32 v83, v84, v85
	v_cvt_pk_bf16_f32 v84, v86, v87
	v_cvt_pk_bf16_f32 v85, v88, v89
	v_add_f32_e32 v252, v252, v86
	v_add_f32_e32 v253, v253, v87
	v_add_f32_e32 v252, v252, v88
	v_add_f32_e32 v253, v253, v89
	s_waitcnt lgkmcnt(4)
	v_mfma_f32_32x32x16_bf16 v[50:65], v[192:195], v[82:85], v[50:65]
	ds_read_b128 v[192:195], v246 offset:16384
	v_exp_f32_e32 v90, v90
	v_exp_f32_e32 v91, v91
	v_exp_f32_e32 v92, v92
	v_exp_f32_e32 v93, v93
	v_exp_f32_e32 v94, v94
	v_mfma_f32_32x32x16_bf16 v[34:49], v[202:205], v[82:85], v[34:49]
	ds_read_b128 v[202:205], v246 offset:20480
	v_exp_f32_e32 v95, v95
	v_exp_f32_e32 v96, v96
	v_exp_f32_e32 v97, v97
	v_add_f32_e32 v252, v252, v90
	v_add_f32_e32 v253, v253, v91
	v_mfma_f32_32x32x16_bf16 v[18:33], v[210:213], v[82:85], v[18:33]
	ds_read_b128 v[210:213], v246 offset:24576
	v_add_f32_e32 v252, v252, v92
	v_add_f32_e32 v253, v253, v93
	v_cvt_pk_bf16_f32 v90, v90, v91
	v_cvt_pk_bf16_f32 v91, v92, v93
	v_cvt_pk_bf16_f32 v92, v94, v95
	v_mfma_f32_32x32x16_bf16 v[2:17], v[218:221], v[82:85], v[2:17]
	ds_read_b128 v[218:221], v246 offset:28672
	v_cvt_pk_bf16_f32 v93, v96, v97
	v_add_f32_e32 v252, v252, v94
	v_add_f32_e32 v253, v253, v95
	v_add_f32_e32 v252, v252, v96
	v_add_f32_e32 v253, v253, v97
	s_waitcnt lgkmcnt(4)
	v_mfma_f32_32x32x16_bf16 v[50:65], v[196:199], v[90:93], v[50:65]
	ds_read_b128 v[196:199], v247 offset:16384
	v_add_f32_e32 v66, v188, v66
	v_add_f32_e32 v67, v188, v67
	v_add_f32_e32 v68, v188, v68
	v_add_f32_e32 v69, v188, v69
	v_add_f32_e32 v70, v188, v70
	v_add_f32_e32 v71, v188, v71
	v_add_f32_e32 v72, v188, v72
	v_mfma_f32_32x32x16_bf16 v[34:49], v[206:209], v[90:93], v[34:49]
	ds_read_b128 v[206:209], v247 offset:20480
	v_add_f32_e32 v73, v188, v73
	v_exp_f32_e32 v66, v66
	v_exp_f32_e32 v67, v67
	v_exp_f32_e32 v68, v68
	v_exp_f32_e32 v69, v69
	v_exp_f32_e32 v70, v70
	v_exp_f32_e32 v71, v71
	v_mfma_f32_32x32x16_bf16 v[18:33], v[214:217], v[90:93], v[18:33]
	ds_read_b128 v[214:217], v247 offset:24576
	v_exp_f32_e32 v72, v72
	v_exp_f32_e32 v73, v73
	v_add_f32_e32 v252, v252, v66
	v_add_f32_e32 v253, v253, v67
	v_add_f32_e32 v252, v252, v68
	v_add_f32_e32 v253, v253, v69
	v_cvt_pk_bf16_f32 v66, v66, v67
	v_mfma_f32_32x32x16_bf16 v[2:17], v[222:225], v[90:93], v[2:17]
	ds_read_b128 v[222:225], v247 offset:28672
	v_cvt_pk_bf16_f32 v67, v68, v69
	v_cvt_pk_bf16_f32 v68, v70, v71
	v_cvt_pk_bf16_f32 v69, v72, v73
	v_add_f32_e32 v252, v252, v70
	v_add_f32_e32 v253, v253, v71
	v_add_f32_e32 v252, v252, v72
	v_add_f32_e32 v253, v253, v73
	s_waitcnt lgkmcnt(4)
	v_mfma_f32_32x32x16_bf16 v[50:65], v[192:195], v[66:69], v[50:65]
	v_add_f32_e32 v74, v188, v74
	v_add_f32_e32 v75, v188, v75
	v_add_f32_e32 v76, v188, v76
	v_add_f32_e32 v77, v188, v77
	v_add_f32_e32 v78, v188, v78
	v_add_f32_e32 v79, v188, v79
	v_add_f32_e32 v80, v188, v80
	v_mfma_f32_32x32x16_bf16 v[34:49], v[202:205], v[66:69], v[34:49]
	v_add_f32_e32 v81, v188, v81
	v_exp_f32_e32 v74, v74
	v_exp_f32_e32 v75, v75
	v_exp_f32_e32 v76, v76
	v_exp_f32_e32 v77, v77
	v_exp_f32_e32 v78, v78
	v_exp_f32_e32 v79, v79
	v_mfma_f32_32x32x16_bf16 v[18:33], v[210:213], v[66:69], v[18:33]
	v_exp_f32_e32 v80, v80
	v_exp_f32_e32 v81, v81
	v_add_f32_e32 v252, v252, v74
	v_add_f32_e32 v253, v253, v75
	v_add_f32_e32 v252, v252, v76
	v_add_f32_e32 v253, v253, v77
	v_cvt_pk_bf16_f32 v74, v74, v75
	v_mfma_f32_32x32x16_bf16 v[2:17], v[218:221], v[66:69], v[2:17]
	v_cvt_pk_bf16_f32 v75, v76, v77
	v_cvt_pk_bf16_f32 v76, v78, v79
	v_cvt_pk_bf16_f32 v77, v80, v81
	v_add_f32_e32 v252, v252, v78
	v_add_f32_e32 v253, v253, v79
	v_add_f32_e32 v252, v252, v80
	v_add_f32_e32 v253, v253, v81
	s_waitcnt lgkmcnt(0)
	v_mfma_f32_32x32x16_bf16 v[50:65], v[196:199], v[74:77], v[50:65]
	v_add_f32_e32 v250, v252, v253
	v_add_f32_e32 v191, v191, v250
	v_add_f32_e32 v226, v131, v226
	v_add_f32_e32 v227, v131, v227
	v_add_f32_e32 v228, v131, v228
	v_mfma_f32_32x32x16_bf16 v[34:49], v[206:209], v[74:77], v[34:49]
	v_add_f32_e32 v229, v131, v229
	v_add_f32_e32 v230, v131, v230
	v_add_f32_e32 v231, v131, v231
	v_add_f32_e32 v232, v131, v232
	v_add_f32_e32 v233, v131, v233
	v_mfma_f32_32x32x16_bf16 v[18:33], v[214:217], v[74:77], v[18:33]
	v_add_f32_e32 v234, v131, v234
	v_add_f32_e32 v235, v131, v235
	v_add_f32_e32 v236, v131, v236
	v_add_f32_e32 v237, v131, v237
	v_add_f32_e32 v238, v131, v238
	v_mfma_f32_32x32x16_bf16 v[2:17], v[222:225], v[74:77], v[2:17]
	v_add_f32_e32 v239, v131, v239
	v_add_f32_e32 v240, v131, v240
	v_add_f32_e32 v241, v131, v241
; #define LAS __attribute__((address_space(3)))
; __device__ __forceinline__ int crow(int r, int hi) { return (r & 3) + 8 * (r >> 2) + 4 * hi; }
; #define MFMA32(a, b, c) __builtin_amdgcn_mfma_f32_32x32x16_bf16((a), (b), (c), 0, 0, 0)
; __device__ __forceinline__ void unit(LAS unsigned char* lds, bf16_t* P1, const bf16_t* vaT, int b, int h, int qblk, float lam, const float* subln_w, const float* khalf) {
;     ...
;         if (jj + 3 < NT) { DMA_TILE(j - 3, (stg + 3) & 3); }
;         const LAS unsigned char* kb = lds + stg * STG;
;         stg = (stg + 1) & 3;
;         f32x16 S0, S1;
;         { float slv = sl2; asm volatile("" : "+v"(slv));
; #pragma unroll
;           for (int r = 0; r < 16; ++r) { S0[r] = __builtin_fmaf(slv, (float)((r & 3) + 8 * (r >> 2)), sl2h); S1[r] = S0[r]; } }
; #pragma unroll
;         for (int ks = 0; ks < 4; ++ks) {
;             const bf16x8 a0 = *(const LAS bf16x8*)(kb + koff[ks]);
;             const bf16x8 a1 = *(const LAS bf16x8*)(kb + koff[ks] + 32 * 256);
;             S0 = MFMA32(a0, qf[ks], S0); S1 = MFMA32(a1, qf[ks], S1);
;         }
;         const int kv0 = 64 * j;
;         if (j >= NT - 2) {
; #pragma unroll
;             for (int r = 0; r < 16; ++r) { const int kv = kv0 + crow(r, hi); if (kv > qrow) S0[r] = -INFINITY; if (kv + 32 > qrow) S1[r] = -INFINITY; }
;         }
;         const float tb0 = sl2 * (float)(kv0 - qrow), tb1 = tb0 + sl2 * 32.f;
;         float mx0 = S0[0], mx1 = S1[0];
; #pragma unroll
;         for (int r = 1; r < 16; ++r) { mx0 = fmaxf(mx0, S0[r]); mx1 = fmaxf(mx1, S1[r]); }
;         float mt = fmaxf(mx0 + tb0, mx1 + tb1); mt = fmaxf(mt, __shfl_xor(mt, 32));
;         const bool skip = __all((mt < m - 24.f) || (mt == -INFINITY));
.La_endA0:
	ds_read_b128 v[192:195], v201 offset:32768
	ds_read_b128 v[202:205], v135 offset:32768
	ds_read_b128 v[210:213], v249 offset:32768
	ds_read_b128 v[218:221], v254 offset:32768
	ds_read_b128 v[196:199], v201 offset:40960
	ds_read_b128 v[206:209], v135 offset:40960
	ds_read_b128 v[214:217], v249 offset:40960
	ds_read_b128 v[222:225], v254 offset:40960
	s_add_i32 s5, s81, 3
	s_cmp_ge_u32 s5, s73
	s_cbranch_scc1 .La_qk_nodmaB0
	s_add_i32 s5, s82, 0x18000
	s_and_b32 s5, s5, 0x18000
	s_add_i32 s5, s72, s5
	s_mov_b32 m0, s5
	s_waitcnt lgkmcnt(4)
	v_mfma_f32_32x32x16_bf16 v[82:97], v[192:195], v[98:101], v[226:241]
	global_load_lds_dwordx4 v[140:141], off
	s_add_i32 m0, s5, 0x400
	v_add_f32_e32 v143, v133, v121
	v_mfma_f32_32x32x16_bf16 v[82:97], v[202:205], v[102:105], v[82:97]
	global_load_lds_dwordx4 v[138:139], off
	s_add_i32 m0, s5, 0x4000
	v_max_f32_e32 v143, 0xff7fffff, v143
	v_mfma_f32_32x32x16_bf16 v[82:97], v[210:213], v[106:109], v[82:97]
	global_load_lds_dwordx4 v134, s[44:45]
	s_add_i32 m0, s5, 0x4400
	v_mfma_f32_32x32x16_bf16 v[82:97], v[218:221], v[110:113], v[82:97]
	global_load_lds_dwordx4 v136, s[44:45]
	ds_read_b128 v[192:195], v244 offset:49152
	ds_read_b128 v[202:205], v244 offset:53248
	ds_read_b128 v[210:213], v244 offset:57344
	ds_read_b128 v[218:221], v244 offset:61440
	s_waitcnt lgkmcnt(4)
	v_mfma_f32_32x32x16_bf16 v[66:81], v[196:199], v[98:101], v[226:241]
	s_add_u32 s44, s44, 0xffffff80
	s_addc_u32 s45, s45, -1
	v_lshl_add_u64 v[138:139], v[138:139], 0, s[38:39]
	v_lshl_add_u64 v[140:141], v[140:141], 0, s[38:39]
	v_mfma_f32_32x32x16_bf16 v[66:81], v[206:209], v[102:105], v[66:81]
	v_max3_f32 v0, v82, v83, v84
	v_max3_f32 v0, v0, v85, v86
	v_mfma_f32_32x32x16_bf16 v[66:81], v[214:217], v[106:109], v[66:81]
	v_max3_f32 v0, v0, v87, v88
	v_max3_f32 v0, v0, v89, v90
	v_max3_f32 v0, v0, v91, v92
	v_mfma_f32_32x32x16_bf16 v[66:81], v[222:225], v[110:113], v[66:81]
	v_max3_f32 v0, v0, v93, v94
	v_max3_f32 v0, v0, v95, v96
	v_max_f32_e32 v0, v0, v97
.La_qk_doneB0:
	ds_read_b128 v[196:199], v245 offset:49152
	ds_read_b128 v[206:209], v245 offset:53248
	ds_read_b128 v[214:217], v245 offset:57344
	ds_read_b128 v[222:225], v245 offset:61440
	s_nop 3
	v_add_u32_e32 v243, s100, v189
	v_add_u32_e32 v250, 0x60, v243
	v_add_u32_e32 v251, 64, v243
	v_cmp_le_i32_e32 vcc, v250, v125
	s_nop 6
	v_cndmask_b32_e32 v66, v184, v66, vcc
	v_cmp_lt_i32_e32 vcc, v251, v125
	s_nop 1
	v_cndmask_b32_e32 v83, v184, v83, vcc
	v_cmp_le_i32_e32 vcc, v251, v125
	v_add_u32_e32 v251, 0x61, v243
	s_nop 0
	v_cndmask_b32_e32 v82, v184, v82, vcc
	v_cmp_le_i32_e32 vcc, v251, v125
	v_add_u32_e32 v251, 0x42, v243
	s_nop 0
	v_cndmask_b32_e32 v67, v184, v67, vcc
	v_cmp_le_i32_e32 vcc, v251, v125
	v_add_u32_e32 v251, 0x62, v243
	s_nop 0
	v_cndmask_b32_e32 v84, v184, v84, vcc
	v_cmp_le_i32_e32 vcc, v251, v125
	v_add_u32_e32 v251, 0x43, v243
	s_nop 0
	v_cndmask_b32_e32 v68, v184, v68, vcc
	v_cmp_le_i32_e32 vcc, v251, v125
	v_add_u32_e32 v251, 0x63, v243
	s_nop 0
	v_cndmask_b32_e32 v85, v184, v85, vcc
	v_cmp_le_i32_e32 vcc, v251, v125
	v_add_u32_e32 v251, 0x48, v243
	s_nop 0
	v_cndmask_b32_e32 v69, v184, v69, vcc
	v_cmp_le_i32_e32 vcc, v251, v125
	v_add_u32_e32 v251, 0x68, v243
	s_nop 0
	v_cndmask_b32_e32 v86, v184, v86, vcc
	v_cmp_le_i32_e32 vcc, v251, v125
	v_add_u32_e32 v251, 0x49, v243
	s_nop 0
	v_cndmask_b32_e32 v70, v184, v70, vcc
	v_cmp_le_i32_e32 vcc, v251, v125
	v_add_u32_e32 v251, 0x69, v243
	s_nop 0
	v_cndmask_b32_e32 v87, v184, v87, vcc
	v_cmp_le_i32_e32 vcc, v251, v125
	v_add_u32_e32 v251, 0x4a, v243
	s_nop 0
	v_cndmask_b32_e32 v71, v184, v71, vcc
	v_cmp_le_i32_e32 vcc, v251, v125
	v_add_u32_e32 v251, 0x6a, v243
	s_nop 0
	v_cndmask_b32_e32 v88, v184, v88, vcc
	v_cmp_le_i32_e32 vcc, v251, v125
	v_add_u32_e32 v251, 0x4b, v243
	s_nop 0
	v_cndmask_b32_e32 v72, v184, v72, vcc
	v_cmp_le_i32_e32 vcc, v251, v125
	v_add_u32_e32 v251, 0x6b, v243
	s_nop 0
	v_cndmask_b32_e32 v89, v184, v89, vcc
	v_cmp_le_i32_e32 vcc, v251, v125
	v_add_u32_e32 v251, 0x50, v243
	s_nop 0
	v_cndmask_b32_e32 v73, v184, v73, vcc
	v_cmp_le_i32_e32 vcc, v251, v125
	v_add_u32_e32 v251, 0x70, v243
	s_nop 0
	v_cndmask_b32_e32 v90, v184, v90, vcc
	v_cmp_le_i32_e32 vcc, v251, v125
	v_add_u32_e32 v251, 0x51, v243
	s_nop 0
	v_cndmask_b32_e32 v74, v184, v74, vcc
	v_cmp_le_i32_e32 vcc, v251, v125
	v_add_u32_e32 v251, 0x71, v243
	s_nop 0
	v_cndmask_b32_e32 v91, v184, v91, vcc
	v_cmp_le_i32_e32 vcc, v251, v125
	v_add_u32_e32 v251, 0x52, v243
	s_nop 0
	v_cndmask_b32_e32 v75, v184, v75, vcc
	v_cmp_le_i32_e32 vcc, v251, v125
	v_add_u32_e32 v251, 0x72, v243
	s_nop 0
	v_cndmask_b32_e32 v92, v184, v92, vcc
	v_cmp_le_i32_e32 vcc, v251, v125
	v_add_u32_e32 v251, 0x53, v243
	s_nop 0
	v_cndmask_b32_e32 v76, v184, v76, vcc
	v_cmp_le_i32_e32 vcc, v251, v125
	v_add_u32_e32 v251, 0x73, v243
	s_nop 0
	v_cndmask_b32_e32 v93, v184, v93, vcc
	v_cmp_le_i32_e32 vcc, v251, v125
	v_add_u32_e32 v251, 0x58, v243
	s_nop 0
	v_cndmask_b32_e32 v77, v184, v77, vcc
	v_cmp_le_i32_e32 vcc, v251, v125
	v_add_u32_e32 v251, 0x78, v243
	s_nop 0
	v_cndmask_b32_e32 v94, v184, v94, vcc
	v_cmp_le_i32_e32 vcc, v251, v125
	v_add_u32_e32 v251, 0x59, v243
	s_nop 0
	v_cndmask_b32_e32 v78, v184, v78, vcc
	v_cmp_le_i32_e32 vcc, v251, v125
	v_add_u32_e32 v251, 0x79, v243
	s_nop 0
	v_cndmask_b32_e32 v95, v184, v95, vcc
	v_cmp_le_i32_e32 vcc, v251, v125
	v_add_u32_e32 v251, 0x5a, v243
	s_nop 0
	v_cndmask_b32_e32 v79, v184, v79, vcc
	v_cmp_le_i32_e32 vcc, v251, v125
	v_add_u32_e32 v251, 0x7a, v243
	s_nop 0
	v_cndmask_b32_e32 v96, v184, v96, vcc
	v_cmp_le_i32_e32 vcc, v251, v125
	v_add_u32_e32 v251, 0x5b, v243
	v_add_u32_e32 v243, 0x7b, v243
	v_cndmask_b32_e32 v80, v184, v80, vcc
	v_cmp_le_i32_e32 vcc, v251, v125
	s_nop 1
	v_cndmask_b32_e32 v97, v184, v97, vcc
	v_cmp_le_i32_e32 vcc, v243, v125
	s_nop 1
	v_cndmask_b32_e32 v81, v184, v81, vcc
	v_max3_f32 v0, v82, v83, v84
	v_max3_f32 v0, v0, v85, v86
	v_max3_f32 v0, v0, v87, v88
	v_max3_f32 v0, v0, v89, v90
	v_max3_f32 v0, v0, v91, v92
	v_max3_f32 v0, v0, v93, v94
	v_max3_f32 v0, v0, v95, v96
	v_max_f32_e32 v0, v0, v97
	s_nop 1
	v_max3_f32 v120, v66, v67, v68
	v_max3_f32 v120, v120, v69, v70
	v_max3_f32 v120, v120, v71, v72
	v_max3_f32 v120, v120, v73, v74
	v_max3_f32 v120, v120, v75, v76
	v_max3_f32 v120, v120, v77, v78
	v_max3_f32 v120, v120, v79, v80
	v_max_f32_e32 v120, v120, v81
	v_add_f32_e32 v120, v188, v120
	v_max_f32_e32 v0, v0, v120
	v_add_f32_e32 v0, v132, v0
	v_mov_b32_e32 v120, v0
	s_nop 1
	v_permlane32_swap_b32_e32 v0, v120
	v_max_f32_e32 v0, v0, v120
	v_cmp_lt_f32_e32 vcc, v0, v143
	v_max_f32_e32 v133, v133, v0
	v_mov_b32_e32 v255, v0
	s_andn2_b64 s[2:3], exec, vcc
	s_cbranch_scc0 .La_skipB0
; #define LAS __attribute__((address_space(3)))
; __device__ __forceinline__ unsigned cvtpk(float lo, float hi) { return pg8::cvt_pk_bf16(lo, hi); }
; __device__ __forceinline__ float ex2(float v) { return __builtin_amdgcn_exp2f(v); }
; #define MFMA32(a, b, c) __builtin_amdgcn_mfma_f32_32x32x16_bf16((a), (b), (c), 0, 0, 0)
; __device__ __forceinline__ void unit(LAS unsigned char* lds, bf16_t* P1, const bf16_t* vaT, int b, int h, int qblk, float lam, const float* subln_w, const float* khalf) {
;     ...
;         { float slv = sl2; asm volatile("" : "+v"(slv));
; #pragma unroll
;           for (int r = 0; r < 16; ++r) { S0[r] = __builtin_fmaf(slv, (float)((r & 3) + 8 * (r >> 2)), sl2h); S1[r] = S0[r]; } }
;     ...
;         for (int r = 0; r < 16; r += 2) { f32x2 a = (f32x2){S0[r], S0[r + 1]} + c0, bq = (f32x2){S1[r], S1[r + 1]} + c1;
;             a.x = ex2(a.x); a.y = ex2(a.y); bq.x = ex2(bq.x); bq.y = ex2(bq.y); S0[r] = a.x; S0[r + 1] = a.y; S1[r] = bq.x; S1[r + 1] = bq.y; ps2 = ps2 + a; ps2 = ps2 + bq; }
;         l = l * alpha + (ps2.x + ps2.y);
;         if (__any(alpha != 1.f)) {
; #pragma unroll
;             for (int d = 0; d < 4; ++d) O[d] = O[d] * alpha;
;         }
;         u32x4 pk[2][2];
; #pragma unroll
;         for (int s = 0; s < 2; ++s) {
;             pk[0][s] = (u32x4){cvtpk(S0[8 * s + 0], S0[8 * s + 1]), cvtpk(S0[8 * s + 2], S0[8 * s + 3]), cvtpk(S0[8 * s + 4], S0[8 * s + 5]), cvtpk(S0[8 * s + 6], S0[8 * s + 7])};
;             pk[1][s] = (u32x4){cvtpk(S1[8 * s + 0], S1[8 * s + 1]), cvtpk(S1[8 * s + 2], S1[8 * s + 3]), cvtpk(S1[8 * s + 4], S1[8 * s + 5]), cvtpk(S1[8 * s + 6], S1[8 * s + 7])};
;         }
; #pragma unroll
;         for (int d = 0; d < 4; ++d)
; #pragma unroll
;             for (int t2 = 0; t2 < 2; ++t2)
; #pragma unroll
;                 for (int s = 0; s < 2; ++s) {
;                     const bf16x8 vf = *(const LAS bf16x8*)(kb + voff[2 * t2 + s] + d * 32 * 128);
;                     O[d] = MFMA32(vf, __builtin_bit_cast(bf16x8, pk[t2][s]), O[d]);
;                 }
	v_exp_f32_e32 v82, v82
	v_exp_f32_e32 v83, v83
	v_exp_f32_e32 v84, v84
	v_exp_f32_e32 v85, v85
	v_exp_f32_e32 v86, v86
	v_exp_f32_e32 v87, v87
	v_exp_f32_e32 v88, v88
	v_exp_f32_e32 v89, v89
	v_add_f32_e32 v252, v82, v84
	v_add_f32_e32 v253, v83, v85
	v_cvt_pk_bf16_f32 v82, v82, v83
	v_cvt_pk_bf16_f32 v83, v84, v85
	v_cvt_pk_bf16_f32 v84, v86, v87
	v_cvt_pk_bf16_f32 v85, v88, v89
	v_add_f32_e32 v252, v252, v86
	v_add_f32_e32 v253, v253, v87
	v_add_f32_e32 v252, v252, v88
	v_add_f32_e32 v253, v253, v89
	s_waitcnt lgkmcnt(4)
	v_mfma_f32_32x32x16_bf16 v[50:65], v[192:195], v[82:85], v[50:65]
	ds_read_b128 v[192:195], v246 offset:49152
	v_exp_f32_e32 v90, v90
	v_exp_f32_e32 v91, v91
	v_exp_f32_e32 v92, v92
	v_exp_f32_e32 v93, v93
	v_exp_f32_e32 v94, v94
	v_mfma_f32_32x32x16_bf16 v[34:49], v[202:205], v[82:85], v[34:49]
	ds_read_b128 v[202:205], v246 offset:53248
	v_exp_f32_e32 v95, v95
	v_exp_f32_e32 v96, v96
	v_exp_f32_e32 v97, v97
	v_add_f32_e32 v252, v252, v90
	v_add_f32_e32 v253, v253, v91
	v_mfma_f32_32x32x16_bf16 v[18:33], v[210:213], v[82:85], v[18:33]
	ds_read_b128 v[210:213], v246 offset:57344
	v_add_f32_e32 v252, v252, v92
	v_add_f32_e32 v253, v253, v93
	v_cvt_pk_bf16_f32 v90, v90, v91
	v_cvt_pk_bf16_f32 v91, v92, v93
	v_cvt_pk_bf16_f32 v92, v94, v95
	v_mfma_f32_32x32x16_bf16 v[2:17], v[218:221], v[82:85], v[2:17]
	ds_read_b128 v[218:221], v246 offset:61440
	v_cvt_pk_bf16_f32 v93, v96, v97
	v_add_f32_e32 v252, v252, v94
	v_add_f32_e32 v253, v253, v95
	v_add_f32_e32 v252, v252, v96
	v_add_f32_e32 v253, v253, v97
	s_waitcnt lgkmcnt(4)
	v_mfma_f32_32x32x16_bf16 v[50:65], v[196:199], v[90:93], v[50:65]
	ds_read_b128 v[196:199], v247 offset:49152
	v_add_f32_e32 v66, v188, v66
	v_add_f32_e32 v67, v188, v67
	v_add_f32_e32 v68, v188, v68
	v_add_f32_e32 v69, v188, v69
	v_add_f32_e32 v70, v188, v70
	v_add_f32_e32 v71, v188, v71
	v_add_f32_e32 v72, v188, v72
	v_mfma_f32_32x32x16_bf16 v[34:49], v[206:209], v[90:93], v[34:49]
	ds_read_b128 v[206:209], v247 offset:53248
	v_add_f32_e32 v73, v188, v73
	v_exp_f32_e32 v66, v66
	v_exp_f32_e32 v67, v67
	v_exp_f32_e32 v68, v68
	v_exp_f32_e32 v69, v69
	v_exp_f32_e32 v70, v70
	v_exp_f32_e32 v71, v71
	v_mfma_f32_32x32x16_bf16 v[18:33], v[214:217], v[90:93], v[18:33]
	ds_read_b128 v[214:217], v247 offset:57344
	v_exp_f32_e32 v72, v72
	v_exp_f32_e32 v73, v73
	v_add_f32_e32 v252, v252, v66
	v_add_f32_e32 v253, v253, v67
	v_add_f32_e32 v252, v252, v68
	v_add_f32_e32 v253, v253, v69
	v_cvt_pk_bf16_f32 v66, v66, v67
	v_mfma_f32_32x32x16_bf16 v[2:17], v[222:225], v[90:93], v[2:17]
	ds_read_b128 v[222:225], v247 offset:61440
	v_cvt_pk_bf16_f32 v67, v68, v69
	v_cvt_pk_bf16_f32 v68, v70, v71
	v_cvt_pk_bf16_f32 v69, v72, v73
	v_add_f32_e32 v252, v252, v70
	v_add_f32_e32 v253, v253, v71
	v_add_f32_e32 v252, v252, v72
	v_add_f32_e32 v253, v253, v73
	s_waitcnt lgkmcnt(4)
	v_mfma_f32_32x32x16_bf16 v[50:65], v[192:195], v[66:69], v[50:65]
	v_add_f32_e32 v74, v188, v74
	v_add_f32_e32 v75, v188, v75
	v_add_f32_e32 v76, v188, v76
	v_add_f32_e32 v77, v188, v77
	v_add_f32_e32 v78, v188, v78
	v_add_f32_e32 v79, v188, v79
	v_add_f32_e32 v80, v188, v80
	v_mfma_f32_32x32x16_bf16 v[34:49], v[202:205], v[66:69], v[34:49]
	v_add_f32_e32 v81, v188, v81
	v_exp_f32_e32 v74, v74
	v_exp_f32_e32 v75, v75
	v_exp_f32_e32 v76, v76
	v_exp_f32_e32 v77, v77
	v_exp_f32_e32 v78, v78
	v_exp_f32_e32 v79, v79
	v_mfma_f32_32x32x16_bf16 v[18:33], v[210:213], v[66:69], v[18:33]
	v_exp_f32_e32 v80, v80
	v_exp_f32_e32 v81, v81
	v_add_f32_e32 v252, v252, v74
	v_add_f32_e32 v253, v253, v75
	v_add_f32_e32 v252, v252, v76
	v_add_f32_e32 v253, v253, v77
	v_cvt_pk_bf16_f32 v74, v74, v75
	v_mfma_f32_32x32x16_bf16 v[2:17], v[218:221], v[66:69], v[2:17]
	v_cvt_pk_bf16_f32 v75, v76, v77
	v_cvt_pk_bf16_f32 v76, v78, v79
	v_cvt_pk_bf16_f32 v77, v80, v81
	v_add_f32_e32 v252, v252, v78
	v_add_f32_e32 v253, v253, v79
	v_add_f32_e32 v252, v252, v80
	v_add_f32_e32 v253, v253, v81
	s_waitcnt lgkmcnt(0)
	v_mfma_f32_32x32x16_bf16 v[50:65], v[196:199], v[74:77], v[50:65]
	v_add_f32_e32 v250, v252, v253
	v_add_f32_e32 v191, v191, v250
	v_add_f32_e32 v248, 0xc3000000, v137
	v_fma_f32 v248, v127, v248, -v132
	v_add_f32_e32 v248, v130, v248
	v_mov_b32_e32 v226, v248
	v_mfma_f32_32x32x16_bf16 v[34:49], v[206:209], v[74:77], v[34:49]
	v_add_f32_e32 v227, v248, v127
	v_fma_f32 v228, v127, s22, v248
	v_fma_f32 v229, v127, s23, v248
	v_fma_f32 v230, v127, s24, v248
	v_fma_f32 v231, v127, s25, v248
	v_fma_f32 v232, v127, s26, v248
	v_mfma_f32_32x32x16_bf16 v[18:33], v[214:217], v[74:77], v[18:33]
	v_fma_f32 v233, v127, s27, v248
	v_fma_f32 v234, v127, s28, v248
	v_fma_f32 v235, v127, s29, v248
	v_fma_f32 v236, v127, s30, v248
	v_fma_f32 v237, v127, s31, v248
	v_fma_f32 v238, v127, s34, v248
	v_mfma_f32_32x32x16_bf16 v[2:17], v[222:225], v[74:77], v[2:17]
	v_fma_f32 v239, v127, s35, v248
	v_fma_f32 v240, v127, s36, v248
	v_fma_f32 v241, v127, s37, v248

; __device__ __forceinline__ void unit(LAS unsigned char* lds, bf16_t* P1, const bf16_t* vaT, int b, int h, int qblk, float lam, const float* subln_w, const float* khalf) {
;     ...
;         { const bool done = __all(qbound + sl2 * (float)(64 * j + 63 - qrow) < m - 24.f);
;           if (lane == 0) dflag[(jj & 1) * 8 + wid] = done ? 1 : 0; }
;         if (jj + 2 < NT) asm volatile("s_waitcnt vmcnt(8) lgkmcnt(0)\n\ts_barrier" ::: "memory"); else if (jj + 1 < NT) asm volatile("s_waitcnt vmcnt(4) lgkmcnt(0)\n\ts_barrier" ::: "memory"); else asm volatile("s_waitcnt vmcnt(0) lgkmcnt(0)\n\ts_barrier" ::: "memory");
;         { typedef int i32x4 __attribute__((ext_vector_type(4)));
;           const i32x4 fa = *(const LAS i32x4*)(lds + 4 * STG + (jj & 1) * 32), fb = *(const LAS i32x4*)(lds + 4 * STG + (jj & 1) * 32 + 16);
;           if (((fa[0] + fa[1]) + (fa[2] + fa[3])) + ((fb[0] + fb[1]) + (fb[2] + fb[3])) == 8) break; }
;         if (jj + 3 < NT) { DMA_TILE(j - 3, (stg + 3) & 3); }
;         const LAS unsigned char* kb = lds + stg * STG;
;         stg = (stg + 1) & 3;
;         f32x16 S0, S1;
;         { float slv = sl2; asm volatile("" : "+v"(slv));
; #pragma unroll
;           for (int r = 0; r < 16; ++r) { S0[r] = __builtin_fmaf(slv, (float)((r & 3) + 8 * (r >> 2)), sl2h); S1[r] = S0[r]; } }
; #pragma unroll
;         for (int ks = 0; ks < 4; ++ks) {
;             const bf16x8 a0 = *(const LAS bf16x8*)(kb + koff[ks]);
;             const bf16x8 a1 = *(const LAS bf16x8*)(kb + koff[ks] + 32 * 256);
;             S0 = MFMA32(a0, qf[ks], S0); S1 = MFMA32(a1, qf[ks], S1);
;         }
;         const int kv0 = 64 * j;
;         if (j >= NT - 2) {
; #pragma unroll
;             for (int r = 0; r < 16; ++r) { const int kv = kv0 + crow(r, hi); if (kv > qrow) S0[r] = -INFINITY; if (kv + 32 > qrow) S1[r] = -INFINITY; }
;         }
;         const float tb0 = sl2 * (float)(kv0 - qrow), tb1 = tb0 + sl2 * 32.f;
;         float mx0 = S0[0], mx1 = S1[0];
; #pragma unroll
;         for (int r = 1; r < 16; ++r) { mx0 = fmaxf(mx0, S0[r]); mx1 = fmaxf(mx1, S1[r]); }
;         float mt = fmaxf(mx0 + tb0, mx1 + tb1); mt = fmaxf(mt, __shfl_xor(mt, 32));
;         const bool skip = __all((mt < m - 24.f) || (mt == -INFINITY));
;         if (!skip) {
;         const float mn = fmaxf(m, mt); const float alpha = ex2(m - mn); m = mn;
;         const float c0 = tb0 - mn, c1 = tb1 - mn;
.La_after_bar:
	s_lshl_b32 s82, s80, 15
	s_add_i32 s83, s82, 0x8000
	s_sub_i32 s100, s76, 64
	s_and_b32 s2, s81, 2
	s_lshl_b32 s2, s2, 4
	s_add_i32 s2, s2, 0x20000
	v_mov_b32_e32 v70, s2
	ds_read_b128 v[66:69], v70
	ds_read_b128 v[70:73], v70 offset:16
	v_add3_u32 v201, s82, v129, v151
	v_add3_u32 v135, s82, v185, v151
	v_add3_u32 v249, s82, v186, v151
	v_add3_u32 v254, s82, v187, v151
	ds_read_b128 v[192:195], v201
	ds_read_b128 v[202:205], v135
	ds_read_b128 v[210:213], v249
	ds_read_b128 v[218:221], v254
	ds_read_b128 v[196:199], v201 offset:8192
	ds_read_b128 v[206:209], v135 offset:8192
	ds_read_b128 v[214:217], v249 offset:8192
	ds_read_b128 v[222:225], v254 offset:8192
	s_waitcnt lgkmcnt(8)
	v_add3_u32 v66, v66, v67, v68
	v_add3_u32 v69, v69, v70, v71
	v_add_u32_e32 v72, v72, v73
	v_add3_u32 v66, v66, v69, v72
	v_cmp_eq_u32_e32 vcc, 8, v66
	s_cbranch_vccnz .LBB0_420
	s_add_i32 s5, s81, 2
	s_cmp_ge_u32 s5, s73
	s_cbranch_scc1 .La_qk_nodmaA
	s_add_i32 s5, s82, 0x10000
	s_and_b32 s5, s5, 0x18000
	s_add_i32 s5, s72, s5
	s_mov_b32 m0, s5
	s_waitcnt lgkmcnt(4)
	v_mfma_f32_32x32x16_bf16 v[82:97], v[192:195], v[98:101], v[226:241]
	global_load_lds_dwordx4 v[140:141], off
	s_add_i32 m0, s5, 0x400
	v_add_u32_e32 v244, s82, v168
	v_add_u32_e32 v245, s82, v169
	v_mfma_f32_32x32x16_bf16 v[82:97], v[202:205], v[102:105], v[82:97]
	global_load_lds_dwordx4 v[138:139], off
	s_add_i32 m0, s5, 0x4000
	v_add_u32_e32 v246, s82, v170
	v_add_u32_e32 v247, s82, v171
	v_mfma_f32_32x32x16_bf16 v[82:97], v[210:213], v[106:109], v[82:97]
	global_load_lds_dwordx4 v134, s[44:45]
	s_add_i32 m0, s5, 0x4400
	v_add_f32_e32 v143, v133, v121
	v_max_f32_e32 v143, 0xff7fffff, v143
	v_mfma_f32_32x32x16_bf16 v[82:97], v[218:221], v[110:113], v[82:97]
	global_load_lds_dwordx4 v136, s[44:45]
	v_fma_f32 v255, v188, -2.0, v255
	v_add_f32_e32 v243, 4.0, v143
	ds_read_b128 v[192:195], v244 offset:16384
	ds_read_b128 v[202:205], v244 offset:20480
	ds_read_b128 v[210:213], v244 offset:24576
	ds_read_b128 v[218:221], v244 offset:28672
	s_waitcnt lgkmcnt(4)
	v_mfma_f32_32x32x16_bf16 v[66:81], v[196:199], v[98:101], v[226:241]
	s_add_u32 s44, s44, 0xffffff80
	s_addc_u32 s45, s45, -1
	v_lshl_add_u64 v[138:139], v[138:139], 0, s[38:39]
	v_lshl_add_u64 v[140:141], v[140:141], 0, s[38:39]
	v_mfma_f32_32x32x16_bf16 v[66:81], v[206:209], v[102:105], v[66:81]
	v_max3_f32 v0, v82, v83, v84
	v_max3_f32 v0, v0, v85, v86
	v_max3_f32 v0, v0, v87, v88
	v_max3_f32 v0, v0, v89, v90
	v_exp_f32_e32 v82, v82
	v_exp_f32_e32 v83, v83
	v_mfma_f32_32x32x16_bf16 v[66:81], v[214:217], v[106:109], v[66:81]
	v_exp_f32_e32 v84, v84
	v_exp_f32_e32 v85, v85
	v_exp_f32_e32 v86, v86
	v_exp_f32_e32 v87, v87
	v_max3_f32 v0, v0, v91, v92
	v_mfma_f32_32x32x16_bf16 v[66:81], v[222:225], v[110:113], v[66:81]
	v_exp_f32_e32 v88, v88
	v_exp_f32_e32 v89, v89
	v_max3_f32 v0, v0, v93, v94
	v_max3_f32 v0, v0, v95, v96
	v_max_f32_e32 v0, v0, v97
	v_cmp_ge_f32_e32 vcc, v255, v243

; #define LAS __attribute__((address_space(3)))
; __device__ __forceinline__ unsigned cvtpk(float lo, float hi) { return pg8::cvt_pk_bf16(lo, hi); }
; __device__ __forceinline__ void unit(LAS unsigned char* lds, bf16_t* P1, const bf16_t* vaT, int b, int h, int qblk, float lam, const float* subln_w, const float* khalf) {
;     ...
;         if (jj + 3 < NT) { DMA_TILE(j - 3, (stg + 3) & 3); }
;         const LAS unsigned char* kb = lds + stg * STG;
;         stg = (stg + 1) & 3;
;         f32x16 S0, S1;
;         { float slv = sl2; asm volatile("" : "+v"(slv));
; #pragma unroll
;           for (int r = 0; r < 16; ++r) { S0[r] = __builtin_fmaf(slv, (float)((r & 3) + 8 * (r >> 2)), sl2h); S1[r] = S0[r]; } }
; #pragma unroll
;         for (int ks = 0; ks < 4; ++ks) {
;             const bf16x8 a0 = *(const LAS bf16x8*)(kb + koff[ks]);
;             const bf16x8 a1 = *(const LAS bf16x8*)(kb + koff[ks] + 32 * 256);
;             S0 = MFMA32(a0, qf[ks], S0); S1 = MFMA32(a1, qf[ks], S1);
;         }
;         const int kv0 = 64 * j;
;         if (j >= NT - 2) {
; #pragma unroll
;     ...
;         for (int r = 0; r < 16; r += 2) { f32x2 a = (f32x2){S0[r], S0[r + 1]} + c0, bq = (f32x2){S1[r], S1[r + 1]} + c1;
;             a.x = ex2(a.x); a.y = ex2(a.y); bq.x = ex2(bq.x); bq.y = ex2(bq.y); S0[r] = a.x; S0[r + 1] = a.y; S1[r] = bq.x; S1[r + 1] = bq.y; ps2 = ps2 + a; ps2 = ps2 + bq; }
;         l = l * alpha + (ps2.x + ps2.y);
;         if (__any(alpha != 1.f)) {
; #pragma unroll
;             for (int d = 0; d < 4; ++d) O[d] = O[d] * alpha;
;         }
;         u32x4 pk[2][2];
; #pragma unroll
;         for (int s = 0; s < 2; ++s) {
;             pk[0][s] = (u32x4){cvtpk(S0[8 * s + 0], S0[8 * s + 1]), cvtpk(S0[8 * s + 2], S0[8 * s + 3]), cvtpk(S0[8 * s + 4], S0[8 * s + 5]), cvtpk(S0[8 * s + 6], S0[8 * s + 7])};
;             pk[1][s] = (u32x4){cvtpk(S1[8 * s + 0], S1[8 * s + 1]), cvtpk(S1[8 * s + 2], S1[8 * s + 3]), cvtpk(S1[8 * s + 4], S1[8 * s + 5]), cvtpk(S1[8 * s + 6], S1[8 * s + 7])};
;         }
; #pragma unroll
;         for (int d = 0; d < 4; ++d)
; #pragma unroll
;             for (int t2 = 0; t2 < 2; ++t2)
; #pragma unroll
;                 for (int s = 0; s < 2; ++s) {
;                     const bf16x8 vf = *(const LAS bf16x8*)(kb + voff[2 * t2 + s] + d * 32 * 128);
;                     O[d] = MFMA32(vf, __builtin_bit_cast(bf16x8, pk[t2][s]), O[d]);
;                 }
.La_nomaxA:
	v_add_f32_e32 v252, v82, v84
	v_add_f32_e32 v253, v83, v85
	v_cvt_pk_bf16_f32 v82, v82, v83
	v_cvt_pk_bf16_f32 v83, v84, v85
	v_cvt_pk_bf16_f32 v84, v86, v87
	v_cvt_pk_bf16_f32 v85, v88, v89
	v_add_f32_e32 v252, v252, v86
	v_add_f32_e32 v253, v253, v87
	v_add_f32_e32 v252, v252, v88
	v_add_f32_e32 v253, v253, v89
	s_waitcnt lgkmcnt(4)
	v_mfma_f32_32x32x16_bf16 v[50:65], v[192:195], v[82:85], v[50:65]
	ds_read_b128 v[192:195], v246 offset:16384
	v_exp_f32_e32 v90, v90
	v_exp_f32_e32 v91, v91
	v_exp_f32_e32 v92, v92
	v_exp_f32_e32 v93, v93
	v_exp_f32_e32 v94, v94
	v_mfma_f32_32x32x16_bf16 v[34:49], v[202:205], v[82:85], v[34:49]
	ds_read_b128 v[202:205], v246 offset:20480
	v_exp_f32_e32 v95, v95
	v_exp_f32_e32 v96, v96
	v_exp_f32_e32 v97, v97
	v_add_f32_e32 v252, v252, v90
	v_add_f32_e32 v253, v253, v91
	v_mfma_f32_32x32x16_bf16 v[18:33], v[210:213], v[82:85], v[18:33]
	ds_read_b128 v[210:213], v246 offset:24576
	v_add_f32_e32 v252, v252, v92
	v_add_f32_e32 v253, v253, v93
	v_cvt_pk_bf16_f32 v90, v90, v91
	v_cvt_pk_bf16_f32 v91, v92, v93
	v_cvt_pk_bf16_f32 v92, v94, v95
	v_mfma_f32_32x32x16_bf16 v[2:17], v[218:221], v[82:85], v[2:17]
	ds_read_b128 v[218:221], v246 offset:28672
	v_cvt_pk_bf16_f32 v93, v96, v97
	v_add_f32_e32 v252, v252, v94
	v_add_f32_e32 v253, v253, v95
	v_add_f32_e32 v252, v252, v96
	v_add_f32_e32 v253, v253, v97
	s_waitcnt lgkmcnt(4)
	v_mfma_f32_32x32x16_bf16 v[50:65], v[196:199], v[90:93], v[50:65]
	ds_read_b128 v[196:199], v247 offset:16384
	v_add_f32_e32 v66, v188, v66
	v_add_f32_e32 v67, v188, v67
	v_add_f32_e32 v68, v188, v68
	v_add_f32_e32 v69, v188, v69
	v_add_f32_e32 v70, v188, v70
	v_add_f32_e32 v71, v188, v71
	v_add_f32_e32 v72, v188, v72
	v_mfma_f32_32x32x16_bf16 v[34:49], v[206:209], v[90:93], v[34:49]
	ds_read_b128 v[206:209], v247 offset:20480
	v_add_f32_e32 v73, v188, v73
	v_exp_f32_e32 v66, v66
	v_exp_f32_e32 v67, v67
	v_exp_f32_e32 v68, v68
	v_exp_f32_e32 v69, v69
	v_exp_f32_e32 v70, v70
	v_exp_f32_e32 v71, v71
	v_mfma_f32_32x32x16_bf16 v[18:33], v[214:217], v[90:93], v[18:33]
	ds_read_b128 v[214:217], v247 offset:24576
	v_exp_f32_e32 v72, v72
	v_exp_f32_e32 v73, v73
	v_add_f32_e32 v252, v252, v66
	v_add_f32_e32 v253, v253, v67
	v_add_f32_e32 v252, v252, v68
	v_add_f32_e32 v253, v253, v69
	v_cvt_pk_bf16_f32 v66, v66, v67
	v_mfma_f32_32x32x16_bf16 v[2:17], v[222:225], v[90:93], v[2:17]
	ds_read_b128 v[222:225], v247 offset:28672
	v_cvt_pk_bf16_f32 v67, v68, v69
	v_cvt_pk_bf16_f32 v68, v70, v71
	v_cvt_pk_bf16_f32 v69, v72, v73
	v_add_f32_e32 v252, v252, v70
	v_add_f32_e32 v253, v253, v71
	v_add_f32_e32 v252, v252, v72
	v_add_f32_e32 v253, v253, v73
	s_waitcnt lgkmcnt(4)
	v_mfma_f32_32x32x16_bf16 v[50:65], v[192:195], v[66:69], v[50:65]
	v_add_f32_e32 v74, v188, v74
	v_add_f32_e32 v75, v188, v75
	v_add_f32_e32 v76, v188, v76
	v_add_f32_e32 v77, v188, v77
	v_add_f32_e32 v78, v188, v78
	v_add_f32_e32 v79, v188, v79
	v_add_f32_e32 v80, v188, v80
	v_mfma_f32_32x32x16_bf16 v[34:49], v[202:205], v[66:69], v[34:49]
	v_add_f32_e32 v81, v188, v81
	v_exp_f32_e32 v74, v74
	v_exp_f32_e32 v75, v75
	v_exp_f32_e32 v76, v76
	v_exp_f32_e32 v77, v77
	v_exp_f32_e32 v78, v78
	v_exp_f32_e32 v79, v79
	v_mfma_f32_32x32x16_bf16 v[18:33], v[210:213], v[66:69], v[18:33]
	v_exp_f32_e32 v80, v80
	v_exp_f32_e32 v81, v81
	v_add_f32_e32 v252, v252, v74
	v_add_f32_e32 v253, v253, v75
	v_add_f32_e32 v252, v252, v76
	v_add_f32_e32 v253, v253, v77
	v_cvt_pk_bf16_f32 v74, v74, v75
	v_mfma_f32_32x32x16_bf16 v[2:17], v[218:221], v[66:69], v[2:17]
	v_cvt_pk_bf16_f32 v75, v76, v77
	v_cvt_pk_bf16_f32 v76, v78, v79
	v_cvt_pk_bf16_f32 v77, v80, v81
	v_add_f32_e32 v252, v252, v78
	v_add_f32_e32 v253, v253, v79
	v_add_f32_e32 v252, v252, v80
	v_add_f32_e32 v253, v253, v81
	s_waitcnt lgkmcnt(0)
	v_mfma_f32_32x32x16_bf16 v[50:65], v[196:199], v[74:77], v[50:65]
	v_add_f32_e32 v250, v252, v253
	v_add_f32_e32 v191, v191, v250
	v_add_f32_e32 v226, v131, v226
	v_add_f32_e32 v227, v131, v227
	v_add_f32_e32 v228, v131, v228
	v_mfma_f32_32x32x16_bf16 v[34:49], v[206:209], v[74:77], v[34:49]
	v_add_f32_e32 v229, v131, v229
	v_add_f32_e32 v230, v131, v230
	v_add_f32_e32 v231, v131, v231
	v_add_f32_e32 v232, v131, v232
	v_add_f32_e32 v233, v131, v233
	v_mfma_f32_32x32x16_bf16 v[18:33], v[214:217], v[74:77], v[18:33]
	v_add_f32_e32 v234, v131, v234
	v_add_f32_e32 v235, v131, v235
	v_add_f32_e32 v236, v131, v236
	v_add_f32_e32 v237, v131, v237
	v_add_f32_e32 v238, v131, v238
	v_mfma_f32_32x32x16_bf16 v[2:17], v[222:225], v[74:77], v[2:17]
	v_add_f32_e32 v239, v131, v239
	v_add_f32_e32 v240, v131, v240
	v_add_f32_e32 v241, v131, v241
.La_endA:
	ds_read_b128 v[192:195], v201 offset:32768
	ds_read_b128 v[202:205], v135 offset:32768
	ds_read_b128 v[210:213], v249 offset:32768
	ds_read_b128 v[218:221], v254 offset:32768
	ds_read_b128 v[196:199], v201 offset:40960
	ds_read_b128 v[206:209], v135 offset:40960
	ds_read_b128 v[214:217], v249 offset:40960
	ds_read_b128 v[222:225], v254 offset:40960
	s_add_i32 s5, s81, 3
	s_cmp_ge_u32 s5, s73
	s_cbranch_scc1 .La_qk_nodmaB
	s_add_i32 s5, s82, 0x18000
	s_and_b32 s5, s5, 0x18000
	s_add_i32 s5, s72, s5
	s_mov_b32 m0, s5
	s_waitcnt lgkmcnt(4)
	v_mfma_f32_32x32x16_bf16 v[82:97], v[192:195], v[98:101], v[226:241]
	global_load_lds_dwordx4 v[140:141], off
	s_add_i32 m0, s5, 0x400
	v_add_f32_e32 v143, v133, v121
	v_mfma_f32_32x32x16_bf16 v[82:97], v[202:205], v[102:105], v[82:97]
	global_load_lds_dwordx4 v[138:139], off
	s_add_i32 m0, s5, 0x4000
	v_max_f32_e32 v143, 0xff7fffff, v143
	v_mfma_f32_32x32x16_bf16 v[82:97], v[210:213], v[106:109], v[82:97]
	global_load_lds_dwordx4 v134, s[44:45]
	s_add_i32 m0, s5, 0x4400
	v_fma_f32 v255, v188, -2.0, v255
	v_mfma_f32_32x32x16_bf16 v[82:97], v[218:221], v[110:113], v[82:97]
	global_load_lds_dwordx4 v136, s[44:45]
	v_add_f32_e32 v243, 4.0, v143
	ds_read_b128 v[192:195], v244 offset:49152
	ds_read_b128 v[202:205], v244 offset:53248
	ds_read_b128 v[210:213], v244 offset:57344
	ds_read_b128 v[218:221], v244 offset:61440
	s_waitcnt lgkmcnt(4)
	v_mfma_f32_32x32x16_bf16 v[66:81], v[196:199], v[98:101], v[226:241]
	s_add_u32 s44, s44, 0xffffff80
	s_addc_u32 s45, s45, -1
	v_lshl_add_u64 v[138:139], v[138:139], 0, s[38:39]
	v_lshl_add_u64 v[140:141], v[140:141], 0, s[38:39]
	v_mfma_f32_32x32x16_bf16 v[66:81], v[206:209], v[102:105], v[66:81]
	v_max3_f32 v0, v82, v83, v84
	v_max3_f32 v0, v0, v85, v86
	v_max3_f32 v0, v0, v87, v88
	v_max3_f32 v0, v0, v89, v90
	v_exp_f32_e32 v82, v82
	v_exp_f32_e32 v83, v83
	v_mfma_f32_32x32x16_bf16 v[66:81], v[214:217], v[106:109], v[66:81]
	v_exp_f32_e32 v84, v84
	v_exp_f32_e32 v85, v85
	v_exp_f32_e32 v86, v86
	v_exp_f32_e32 v87, v87
	v_max3_f32 v0, v0, v91, v92
	v_mfma_f32_32x32x16_bf16 v[66:81], v[222:225], v[110:113], v[66:81]
	v_exp_f32_e32 v88, v88
	v_exp_f32_e32 v89, v89
	v_max3_f32 v0, v0, v93, v94
	v_max3_f32 v0, v0, v95, v96
	v_max_f32_e32 v0, v0, v97
	v_cmp_ge_f32_e32 vcc, v255, v243

; #define LAS __attribute__((address_space(3)))
; __device__ __forceinline__ unsigned cvtpk(float lo, float hi) { return pg8::cvt_pk_bf16(lo, hi); }
; __device__ __forceinline__ float ex2(float v) { return __builtin_amdgcn_exp2f(v); }
; #define MFMA32(a, b, c) __builtin_amdgcn_mfma_f32_32x32x16_bf16((a), (b), (c), 0, 0, 0)
; __device__ __forceinline__ void unit(LAS unsigned char* lds, bf16_t* P1, const bf16_t* vaT, int b, int h, int qblk, float lam, const float* subln_w, const float* khalf) {
;     ...
;         { float slv = sl2; asm volatile("" : "+v"(slv));
; #pragma unroll
;           for (int r = 0; r < 16; ++r) { S0[r] = __builtin_fmaf(slv, (float)((r & 3) + 8 * (r >> 2)), sl2h); S1[r] = S0[r]; } }
;     ...
;         for (int r = 0; r < 16; r += 2) { f32x2 a = (f32x2){S0[r], S0[r + 1]} + c0, bq = (f32x2){S1[r], S1[r + 1]} + c1;
;             a.x = ex2(a.x); a.y = ex2(a.y); bq.x = ex2(bq.x); bq.y = ex2(bq.y); S0[r] = a.x; S0[r + 1] = a.y; S1[r] = bq.x; S1[r + 1] = bq.y; ps2 = ps2 + a; ps2 = ps2 + bq; }
;         l = l * alpha + (ps2.x + ps2.y);
;         if (__any(alpha != 1.f)) {
; #pragma unroll
;             for (int d = 0; d < 4; ++d) O[d] = O[d] * alpha;
;         }
;         u32x4 pk[2][2];
; #pragma unroll
;         for (int s = 0; s < 2; ++s) {
;             pk[0][s] = (u32x4){cvtpk(S0[8 * s + 0], S0[8 * s + 1]), cvtpk(S0[8 * s + 2], S0[8 * s + 3]), cvtpk(S0[8 * s + 4], S0[8 * s + 5]), cvtpk(S0[8 * s + 6], S0[8 * s + 7])};
;             pk[1][s] = (u32x4){cvtpk(S1[8 * s + 0], S1[8 * s + 1]), cvtpk(S1[8 * s + 2], S1[8 * s + 3]), cvtpk(S1[8 * s + 4], S1[8 * s + 5]), cvtpk(S1[8 * s + 6], S1[8 * s + 7])};
;         }
; #pragma unroll
;         for (int d = 0; d < 4; ++d)
; #pragma unroll
;             for (int t2 = 0; t2 < 2; ++t2)
; #pragma unroll
;                 for (int s = 0; s < 2; ++s) {
;                     const bf16x8 vf = *(const LAS bf16x8*)(kb + voff[2 * t2 + s] + d * 32 * 128);
;                     O[d] = MFMA32(vf, __builtin_bit_cast(bf16x8, pk[t2][s]), O[d]);
;                 }
.La_nomaxB:
	v_add_f32_e32 v252, v82, v84
	v_add_f32_e32 v253, v83, v85
	v_cvt_pk_bf16_f32 v82, v82, v83
	v_cvt_pk_bf16_f32 v83, v84, v85
	v_cvt_pk_bf16_f32 v84, v86, v87
	v_cvt_pk_bf16_f32 v85, v88, v89
	v_add_f32_e32 v252, v252, v86
	v_add_f32_e32 v253, v253, v87
	v_add_f32_e32 v252, v252, v88
	v_add_f32_e32 v253, v253, v89
	s_waitcnt lgkmcnt(4)
	v_mfma_f32_32x32x16_bf16 v[50:65], v[192:195], v[82:85], v[50:65]
	ds_read_b128 v[192:195], v246 offset:49152
	v_exp_f32_e32 v90, v90
	v_exp_f32_e32 v91, v91
	v_exp_f32_e32 v92, v92
	v_exp_f32_e32 v93, v93
	v_exp_f32_e32 v94, v94
	v_mfma_f32_32x32x16_bf16 v[34:49], v[202:205], v[82:85], v[34:49]
	ds_read_b128 v[202:205], v246 offset:53248
	v_exp_f32_e32 v95, v95
	v_exp_f32_e32 v96, v96
	v_exp_f32_e32 v97, v97
	v_add_f32_e32 v252, v252, v90
	v_add_f32_e32 v253, v253, v91
	v_mfma_f32_32x32x16_bf16 v[18:33], v[210:213], v[82:85], v[18:33]
	ds_read_b128 v[210:213], v246 offset:57344
	v_add_f32_e32 v252, v252, v92
	v_add_f32_e32 v253, v253, v93
	v_cvt_pk_bf16_f32 v90, v90, v91
	v_cvt_pk_bf16_f32 v91, v92, v93
	v_cvt_pk_bf16_f32 v92, v94, v95
	v_mfma_f32_32x32x16_bf16 v[2:17], v[218:221], v[82:85], v[2:17]
	ds_read_b128 v[218:221], v246 offset:61440
	v_cvt_pk_bf16_f32 v93, v96, v97
	v_add_f32_e32 v252, v252, v94
	v_add_f32_e32 v253, v253, v95
	v_add_f32_e32 v252, v252, v96
	v_add_f32_e32 v253, v253, v97
	s_waitcnt lgkmcnt(4)
	v_mfma_f32_32x32x16_bf16 v[50:65], v[196:199], v[90:93], v[50:65]
	ds_read_b128 v[196:199], v247 offset:49152
	v_add_f32_e32 v66, v188, v66
	v_add_f32_e32 v67, v188, v67
	v_add_f32_e32 v68, v188, v68
	v_add_f32_e32 v69, v188, v69
	v_add_f32_e32 v70, v188, v70
	v_add_f32_e32 v71, v188, v71
	v_add_f32_e32 v72, v188, v72
	v_mfma_f32_32x32x16_bf16 v[34:49], v[206:209], v[90:93], v[34:49]
	ds_read_b128 v[206:209], v247 offset:53248
	v_add_f32_e32 v73, v188, v73
	v_exp_f32_e32 v66, v66
	v_exp_f32_e32 v67, v67
	v_exp_f32_e32 v68, v68
	v_exp_f32_e32 v69, v69
	v_exp_f32_e32 v70, v70
	v_exp_f32_e32 v71, v71
	v_mfma_f32_32x32x16_bf16 v[18:33], v[214:217], v[90:93], v[18:33]
	ds_read_b128 v[214:217], v247 offset:57344
	v_exp_f32_e32 v72, v72
	v_exp_f32_e32 v73, v73
	v_add_f32_e32 v252, v252, v66
	v_add_f32_e32 v253, v253, v67
	v_add_f32_e32 v252, v252, v68
	v_add_f32_e32 v253, v253, v69
	v_cvt_pk_bf16_f32 v66, v66, v67
	v_mfma_f32_32x32x16_bf16 v[2:17], v[222:225], v[90:93], v[2:17]
	ds_read_b128 v[222:225], v247 offset:61440
	v_cvt_pk_bf16_f32 v67, v68, v69
	v_cvt_pk_bf16_f32 v68, v70, v71
	v_cvt_pk_bf16_f32 v69, v72, v73
	v_add_f32_e32 v252, v252, v70
	v_add_f32_e32 v253, v253, v71
	v_add_f32_e32 v252, v252, v72
	v_add_f32_e32 v253, v253, v73
	s_waitcnt lgkmcnt(4)
	v_mfma_f32_32x32x16_bf16 v[50:65], v[192:195], v[66:69], v[50:65]
	v_add_f32_e32 v74, v188, v74
	v_add_f32_e32 v75, v188, v75
	v_add_f32_e32 v76, v188, v76
	v_add_f32_e32 v77, v188, v77
	v_add_f32_e32 v78, v188, v78
	v_add_f32_e32 v79, v188, v79
	v_add_f32_e32 v80, v188, v80
	v_mfma_f32_32x32x16_bf16 v[34:49], v[202:205], v[66:69], v[34:49]
	v_add_f32_e32 v81, v188, v81
	v_exp_f32_e32 v74, v74
	v_exp_f32_e32 v75, v75
	v_exp_f32_e32 v76, v76
	v_exp_f32_e32 v77, v77
	v_exp_f32_e32 v78, v78
	v_exp_f32_e32 v79, v79
	v_mfma_f32_32x32x16_bf16 v[18:33], v[210:213], v[66:69], v[18:33]
	v_exp_f32_e32 v80, v80
	v_exp_f32_e32 v81, v81
	v_add_f32_e32 v252, v252, v74
	v_add_f32_e32 v253, v253, v75
	v_add_f32_e32 v252, v252, v76
	v_add_f32_e32 v253, v253, v77
	v_cvt_pk_bf16_f32 v74, v74, v75
	v_mfma_f32_32x32x16_bf16 v[2:17], v[218:221], v[66:69], v[2:17]
	v_cvt_pk_bf16_f32 v75, v76, v77
	v_cvt_pk_bf16_f32 v76, v78, v79
	v_cvt_pk_bf16_f32 v77, v80, v81
	v_add_f32_e32 v252, v252, v78
	v_add_f32_e32 v253, v253, v79
	v_add_f32_e32 v252, v252, v80
	v_add_f32_e32 v253, v253, v81
	s_waitcnt lgkmcnt(0)
	v_mfma_f32_32x32x16_bf16 v[50:65], v[196:199], v[74:77], v[50:65]
	v_add_f32_e32 v250, v252, v253
	v_add_f32_e32 v191, v191, v250
	v_add_f32_e32 v248, 0xc3000000, v137
	v_fma_f32 v248, v127, v248, -v132
	v_add_f32_e32 v248, v130, v248
	v_mov_b32_e32 v226, v248
	v_mfma_f32_32x32x16_bf16 v[34:49], v[206:209], v[74:77], v[34:49]
	v_add_f32_e32 v227, v248, v127
	v_fma_f32 v228, v127, s22, v248
	v_fma_f32 v229, v127, s23, v248
	v_fma_f32 v230, v127, s24, v248
	v_fma_f32 v231, v127, s25, v248
	v_fma_f32 v232, v127, s26, v248
	v_mfma_f32_32x32x16_bf16 v[18:33], v[214:217], v[74:77], v[18:33]
	v_fma_f32 v233, v127, s27, v248
	v_fma_f32 v234, v127, s28, v248
	v_fma_f32 v235, v127, s29, v248
	v_fma_f32 v236, v127, s30, v248
	v_fma_f32 v237, v127, s31, v248
	v_fma_f32 v238, v127, s34, v248
	v_mfma_f32_32x32x16_bf16 v[2:17], v[222:225], v[74:77], v[2:17]
	v_fma_f32 v239, v127, s35, v248
	v_fma_f32 v240, v127, s36, v248
	v_fma_f32 v241, v127, s37, v248

; __device__ __forceinline__ float ex2(float v) { return __builtin_amdgcn_exp2f(v); }
; __device__ __forceinline__ void unit(LAS unsigned char* lds, bf16_t* P1, const bf16_t* vaT, int b, int h, int qblk, float lam, const float* subln_w, const float* khalf) {
;     ...
;         const float tb0 = sl2 * (float)(kv0 - qrow), tb1 = tb0 + sl2 * 32.f;
;         float mx0 = S0[0], mx1 = S1[0];
; #pragma unroll
;         for (int r = 1; r < 16; ++r) { mx0 = fmaxf(mx0, S0[r]); mx1 = fmaxf(mx1, S1[r]); }
;         float mt = fmaxf(mx0 + tb0, mx1 + tb1); mt = fmaxf(mt, __shfl_xor(mt, 32));
;         const bool skip = __all((mt < m - 24.f) || (mt == -INFINITY));
;         if (!skip) {
;         const float mn = fmaxf(m, mt); const float alpha = ex2(m - mn); m = mn;
;         const float c0 = tb0 - mn, c1 = tb1 - mn;
;         f32x2 ps2 = (f32x2){0.f, 0.f};
; #pragma unroll
;         for (int r = 0; r < 16; r += 2) { f32x2 a = (f32x2){S0[r], S0[r + 1]} + c0, bq = (f32x2){S1[r], S1[r + 1]} + c1;
;             a.x = ex2(a.x); a.y = ex2(a.y); bq.x = ex2(bq.x); bq.y = ex2(bq.y); S0[r] = a.x; S0[r + 1] = a.y; S1[r] = bq.x; S1[r + 1] = bq.y; ps2 = ps2 + a; ps2 = ps2 + bq; }
.La_skipA0:
	v_add_f32_e32 v226, v131, v226
	v_add_f32_e32 v227, v131, v227
	v_add_f32_e32 v228, v131, v228
	v_add_f32_e32 v229, v131, v229
	v_add_f32_e32 v230, v131, v230
	v_add_f32_e32 v231, v131, v231
	v_add_f32_e32 v232, v131, v232
	v_add_f32_e32 v233, v131, v233
	v_add_f32_e32 v234, v131, v234
	v_add_f32_e32 v235, v131, v235
	v_add_f32_e32 v236, v131, v236
	v_add_f32_e32 v237, v131, v237
	v_add_f32_e32 v238, v131, v238
	v_add_f32_e32 v239, v131, v239
	v_add_f32_e32 v240, v131, v240
	v_add_f32_e32 v241, v131, v241
	s_branch .La_endA0
.La_qk_nodmaB0:
	s_waitcnt lgkmcnt(4)
	v_mfma_f32_32x32x16_bf16 v[82:97], v[192:195], v[98:101], v[226:241]
	v_add_f32_e32 v143, v133, v121
	v_mfma_f32_32x32x16_bf16 v[82:97], v[202:205], v[102:105], v[82:97]
	v_max_f32_e32 v143, 0xff7fffff, v143
	v_mfma_f32_32x32x16_bf16 v[82:97], v[210:213], v[106:109], v[82:97]
	v_mfma_f32_32x32x16_bf16 v[82:97], v[218:221], v[110:113], v[82:97]
	ds_read_b128 v[192:195], v244 offset:49152
	ds_read_b128 v[202:205], v244 offset:53248
	ds_read_b128 v[210:213], v244 offset:57344
	ds_read_b128 v[218:221], v244 offset:61440
	s_waitcnt lgkmcnt(4)
	v_mfma_f32_32x32x16_bf16 v[66:81], v[196:199], v[98:101], v[226:241]
	v_mfma_f32_32x32x16_bf16 v[66:81], v[206:209], v[102:105], v[66:81]
	v_max3_f32 v0, v82, v83, v84
	v_max3_f32 v0, v0, v85, v86
	v_mfma_f32_32x32x16_bf16 v[66:81], v[214:217], v[106:109], v[66:81]
	v_max3_f32 v0, v0, v87, v88
	v_max3_f32 v0, v0, v89, v90
	v_max3_f32 v0, v0, v91, v92
	v_mfma_f32_32x32x16_bf16 v[66:81], v[222:225], v[110:113], v[66:81]
	v_max3_f32 v0, v0, v93, v94
	v_max3_f32 v0, v0, v95, v96
	v_max_f32_e32 v0, v0, v97
	s_branch .La_qk_doneB0
.La_skipB0:
	v_add_f32_e32 v248, 0xc3000000, v137
	v_fma_f32 v248, v127, v248, -v132
	v_add_f32_e32 v248, v130, v248
	v_mov_b32_e32 v226, v248
	v_add_f32_e32 v227, v248, v127
	v_fma_f32 v228, v127, s22, v248
	v_fma_f32 v229, v127, s23, v248
	v_fma_f32 v230, v127, s24, v248
	v_fma_f32 v231, v127, s25, v248
	v_fma_f32 v232, v127, s26, v248
	v_fma_f32 v233, v127, s27, v248
	v_fma_f32 v234, v127, s28, v248
	v_fma_f32 v235, v127, s29, v248
	v_fma_f32 v236, v127, s30, v248
	v_fma_f32 v237, v127, s31, v248
	v_fma_f32 v238, v127, s34, v248
	v_fma_f32 v239, v127, s35, v248
	v_fma_f32 v240, v127, s36, v248
	v_fma_f32 v241, v127, s37, v248
	s_branch .La_endB0
.La_qk_nodmaA:
	s_waitcnt lgkmcnt(4)
	v_mfma_f32_32x32x16_bf16 v[82:97], v[192:195], v[98:101], v[226:241]
	v_add_u32_e32 v244, s82, v168
	v_add_u32_e32 v245, s82, v169
	v_mfma_f32_32x32x16_bf16 v[82:97], v[202:205], v[102:105], v[82:97]
	v_add_u32_e32 v246, s82, v170
	v_add_u32_e32 v247, s82, v171
	v_mfma_f32_32x32x16_bf16 v[82:97], v[210:213], v[106:109], v[82:97]
	v_add_f32_e32 v143, v133, v121
	v_max_f32_e32 v143, 0xff7fffff, v143
	v_mfma_f32_32x32x16_bf16 v[82:97], v[218:221], v[110:113], v[82:97]
	v_fma_f32 v255, v188, -2.0, v255
	v_add_f32_e32 v243, 4.0, v143
	ds_read_b128 v[192:195], v244 offset:16384
	ds_read_b128 v[202:205], v244 offset:20480
	ds_read_b128 v[210:213], v244 offset:24576
	ds_read_b128 v[218:221], v244 offset:28672
	s_waitcnt lgkmcnt(4)
	v_mfma_f32_32x32x16_bf16 v[66:81], v[196:199], v[98:101], v[226:241]
	v_mfma_f32_32x32x16_bf16 v[66:81], v[206:209], v[102:105], v[66:81]
	v_max3_f32 v0, v82, v83, v84
	v_max3_f32 v0, v0, v85, v86
	v_max3_f32 v0, v0, v87, v88
	v_max3_f32 v0, v0, v89, v90
	v_exp_f32_e32 v82, v82
	v_exp_f32_e32 v83, v83
	v_mfma_f32_32x32x16_bf16 v[66:81], v[214:217], v[106:109], v[66:81]
	v_exp_f32_e32 v84, v84
	v_exp_f32_e32 v85, v85
	v_exp_f32_e32 v86, v86
	v_exp_f32_e32 v87, v87
	v_max3_f32 v0, v0, v91, v92
	v_mfma_f32_32x32x16_bf16 v[66:81], v[222:225], v[110:113], v[66:81]
	v_exp_f32_e32 v88, v88
	v_exp_f32_e32 v89, v89
	v_max3_f32 v0, v0, v93, v94
	v_max3_f32 v0, v0, v95, v96
	v_max_f32_e32 v0, v0, v97
	v_cmp_ge_f32_e32 vcc, v255, v243
	s_branch .La_qk_doneA
.La_maxA:
	s_nop 1
	v_max3_f32 v120, v66, v67, v68
	v_max3_f32 v120, v120, v69, v70
	v_max3_f32 v120, v120, v71, v72
	v_max3_f32 v120, v120, v73, v74
	v_max3_f32 v120, v120, v75, v76
	v_max3_f32 v120, v120, v77, v78
	v_max3_f32 v120, v120, v79, v80
	v_max_f32_e32 v120, v120, v81
	v_add_f32_e32 v120, v188, v120
	v_max_f32_e32 v0, v0, v120
	v_add_f32_e32 v0, v132, v0
	v_mov_b32_e32 v120, v0
	s_nop 1
	v_permlane32_swap_b32_e32 v0, v120
	v_max_f32_e32 v0, v0, v120
	v_cmp_lt_f32_e32 vcc, v0, v143
	v_max_f32_e32 v133, v133, v0
	v_mov_b32_e32 v255, v0
	s_andn2_b64 s[2:3], exec, vcc
	s_cbranch_scc0 .La_skipA
	s_branch .La_nomaxA

; #define LAS __attribute__((address_space(3)))
; __device__ __forceinline__ int crow(int r, int hi) { return (r & 3) + 8 * (r >> 2) + 4 * hi; }
; __device__ __forceinline__ float ex2(float v) { return __builtin_amdgcn_exp2f(v); }
; #define MFMA32(a, b, c) __builtin_amdgcn_mfma_f32_32x32x16_bf16((a), (b), (c), 0, 0, 0)
; __device__ __forceinline__ void unit(LAS unsigned char* lds, bf16_t* P1, const bf16_t* vaT, int b, int h, int qblk, float lam, const float* subln_w, const float* khalf) {
;     ...
;         for (int ks = 0; ks < 4; ++ks) {
;             const bf16x8 a0 = *(const LAS bf16x8*)(kb + koff[ks]);
;             const bf16x8 a1 = *(const LAS bf16x8*)(kb + koff[ks] + 32 * 256);
;             S0 = MFMA32(a0, qf[ks], S0); S1 = MFMA32(a1, qf[ks], S1);
;         }
;         const int kv0 = 64 * j;
;         if (j >= NT - 2) {
; #pragma unroll
;             for (int r = 0; r < 16; ++r) { const int kv = kv0 + crow(r, hi); if (kv > qrow) S0[r] = -INFINITY; if (kv + 32 > qrow) S1[r] = -INFINITY; }
;         }
;         const float tb0 = sl2 * (float)(kv0 - qrow), tb1 = tb0 + sl2 * 32.f;
;         float mx0 = S0[0], mx1 = S1[0];
; #pragma unroll
;         for (int r = 1; r < 16; ++r) { mx0 = fmaxf(mx0, S0[r]); mx1 = fmaxf(mx1, S1[r]); }
;         float mt = fmaxf(mx0 + tb0, mx1 + tb1); mt = fmaxf(mt, __shfl_xor(mt, 32));
;         const bool skip = __all((mt < m - 24.f) || (mt == -INFINITY));
;         if (!skip) {
;         const float mn = fmaxf(m, mt); const float alpha = ex2(m - mn); m = mn;
;         const float c0 = tb0 - mn, c1 = tb1 - mn;
;         f32x2 ps2 = (f32x2){0.f, 0.f};
; #pragma unroll
;         for (int r = 0; r < 16; r += 2) { f32x2 a = (f32x2){S0[r], S0[r + 1]} + c0, bq = (f32x2){S1[r], S1[r + 1]} + c1;
;             a.x = ex2(a.x); a.y = ex2(a.y); bq.x = ex2(bq.x); bq.y = ex2(bq.y); S0[r] = a.x; S0[r + 1] = a.y; S1[r] = bq.x; S1[r + 1] = bq.y; ps2 = ps2 + a; ps2 = ps2 + bq; }
.La_qk_nodmaB:
	s_waitcnt lgkmcnt(4)
	v_mfma_f32_32x32x16_bf16 v[82:97], v[192:195], v[98:101], v[226:241]
	v_add_f32_e32 v143, v133, v121
	v_mfma_f32_32x32x16_bf16 v[82:97], v[202:205], v[102:105], v[82:97]
	v_max_f32_e32 v143, 0xff7fffff, v143
	v_mfma_f32_32x32x16_bf16 v[82:97], v[210:213], v[106:109], v[82:97]
	v_fma_f32 v255, v188, -2.0, v255
	v_mfma_f32_32x32x16_bf16 v[82:97], v[218:221], v[110:113], v[82:97]
	v_add_f32_e32 v243, 4.0, v143
	ds_read_b128 v[192:195], v244 offset:49152
	ds_read_b128 v[202:205], v244 offset:53248
	ds_read_b128 v[210:213], v244 offset:57344
	ds_read_b128 v[218:221], v244 offset:61440
	s_waitcnt lgkmcnt(4)
	v_mfma_f32_32x32x16_bf16 v[66:81], v[196:199], v[98:101], v[226:241]
	v_mfma_f32_32x32x16_bf16 v[66:81], v[206:209], v[102:105], v[66:81]
	v_max3_f32 v0, v82, v83, v84
	v_max3_f32 v0, v0, v85, v86
	v_max3_f32 v0, v0, v87, v88
	v_max3_f32 v0, v0, v89, v90
	v_exp_f32_e32 v82, v82
	v_exp_f32_e32 v83, v83
	v_mfma_f32_32x32x16_bf16 v[66:81], v[214:217], v[106:109], v[66:81]
	v_exp_f32_e32 v84, v84
	v_exp_f32_e32 v85, v85
	v_exp_f32_e32 v86, v86
	v_exp_f32_e32 v87, v87
	v_max3_f32 v0, v0, v91, v92
	v_mfma_f32_32x32x16_bf16 v[66:81], v[222:225], v[110:113], v[66:81]
	v_exp_f32_e32 v88, v88
	v_exp_f32_e32 v89, v89
	v_max3_f32 v0, v0, v93, v94
	v_max3_f32 v0, v0, v95, v96
	v_max_f32_e32 v0, v0, v97
	v_cmp_ge_f32_e32 vcc, v255, v243
	s_branch .La_qk_doneB
